# AD (ATTUP->RWUP) and GT (gate GEMM -> ATTUP/RWUP epilogues) intermediates also stored lane-linear (coalesced 1KB bursts), on top of x1/PP
# speedup vs baseline: 1.0196x; 1.0022x over previous
;     __device__ __forceinline__ void operator()(const i32x4 (&acc)[2][2][4][2], const Unit& uu, int wr, int wc, int fr, int fq) const {
;         Unit u = uu; u.pn += pn0;
;         const int row0 = u.pm * BM + wr * 64 + fr, cl = wc * 32 + 8 * fq;
;         bf16_t* base; int ldc, colt; bool sg = false;
;         if (u.pn < 18) { base = QKV; ldc = 4608; colt = u.pn * 256; }
;         else if (u.pn < 44) { base = Z; ldc = 6656; colt = (u.pn - 18) * 256; }
;         else { base = GT; ldc = 8192; colt = (u.pn - 44) * 256; sg = true; }
;         const int col0 = colt + cl;
.LBB0_610:
	s_lshl_b32 s98, s6, 5
	s_add_i32 s98, s98, s30
	s_lshl_b32 s98, s98, 17
	v_and_b32_e32 v248, 63, v0
	v_lshlrev_b32_e32 v248, 4, v248
	v_lshrrev_b32_e32 v249, 6, v0
	v_lshl_add_u32 v248, v249, 14, v248
	v_add_u32_e32 v248, s98, v248
	v_mov_b32_e32 v249, 0
	v_lshl_add_u64 v[248:249], s[12:13], 0, v[248:249]
	s_add_i32 s7, s30, 44
	v_mov_b32_e32 v58, v0
	s_cmpk_gt_i32 s30, 0xffe5
	s_mov_b64 s[40:41], -1
	s_cbranch_scc0 .LBB0_616
	s_lshl_b32 s38, s7, 8
	s_cmp_lt_u32 s30, 0xffffffd4
	s_mov_b64 s[36:37], -1
	s_mov_b64 s[30:31], -1
	s_cbranch_scc0 .LBB0_613
	s_add_i32 s9, s38, 0xffffd400
	s_mov_b64 s[30:31], 0

; __device__ __forceinline__ u32x4 pack8(const f32x4 v0, const f32x4 v1) { u32x4 w; w.x = cvt_pk_bf16(v0[0], v0[1]); w.y = cvt_pk_bf16(v0[2], v0[3]); w.z = cvt_pk_bf16(v1[0], v1[1]); w.w = cvt_pk_bf16(v1[2], v1[3]); return w; }
; __device__ __forceinline__ f32x4 sig4(const f32x4 v) { return (f32x4){sigmoidf_(v[0]), sigmoidf_(v[1]), sigmoidf_(v[2]), sigmoidf_(v[3])}; }
;     __device__ __forceinline__ void operator()(const i32x4 (&acc)[2][2][4][2], const Unit& uu, int wr, int wc, int fr, int fq) const {
;     ...
;         for (int ai = 0; ai < 2; ++ai)
; #pragma unroll
;             for (int m = 0; m < 4; ++m) { const int r = row0 + ai * HALF + m * 16; const float rs = rsv[ai][m]; bf16_t* rowp = base + (size_t)r * ldc + col0;
; #pragma unroll
;                 for (int bj = 0; bj < 2; ++bj) { f32x4 v0 = __builtin_convertvector(acc[ai][bj][m][0], f32x4) * rs * sv[bj][0], v1 = __builtin_convertvector(acc[ai][bj][m][1], f32x4) * rs * sv[bj][1];
;                     if (sg) { v0 = sig4(v0); v1 = sig4(v1); }
;                     *(u32x4*)(rowp + bj * HALF) = pack8(v0, v1); } }
.LBB0_620:
	v_cvt_f32_i32_e32 v135, v135
	v_cvt_f32_i32_e32 v137, v137
	v_cvt_f32_i32_e32 v136, v136
	v_cvt_f32_i32_e32 v134, v134
	v_cvt_f32_i32_e32 v131, v131
	v_cvt_f32_i32_e32 v133, v133
	v_cvt_f32_i32_e32 v132, v132
	v_cvt_f32_i32_e32 v130, v130
	v_add_u32_e32 v138, s9, v194
	v_mov_b32_e32 v143, v142
	v_ashrrev_i32_e32 v139, 31, v138
	v_mul_lo_u32 v194, s3, v162
	v_mul_lo_u32 v163, s2, v163
	v_mad_u64_u32 v[140:141], s[30:31], s2, v162, 0
	s_nop 0
	v_cvt_pk_bf16_f32 v172, v172, v173
	s_nop 0
	v_cvt_pk_bf16_f32 v173, v170, v171
	s_nop 0
	v_cvt_pk_bf16_f32 v174, v174, v175
	s_nop 0
	v_cvt_pk_bf16_f32 v175, v144, v145
	v_mov_b32_e32 v144, v142
	v_mov_b32_e32 v145, v142
	v_lshl_add_u64 v[138:139], v[138:139], 1, s[34:35]
	v_add3_u32 v141, v141, v163, v194
	v_pk_mul_f32 v[136:137], v[144:145], v[136:137]
	v_pk_mul_f32 v[170:171], v[142:143], v[134:135]
	v_pk_mul_f32 v[132:133], v[144:145], v[132:133]
	v_pk_mul_f32 v[130:131], v[142:143], v[130:131]
	s_mov_b64 s[98:99], 0x0
	v_lshl_add_u64 v[140:141], v[248:249], 0, s[98:99]
	v_pk_mul_f32 v[134:135], v[64:65], v[136:137]
	v_pk_mul_f32 v[136:137], v[62:63], v[170:171]
	v_pk_mul_f32 v[132:133], v[60:61], v[132:133]
	s_and_b64 vcc, exec, s[6:7]
	v_pk_mul_f32 v[142:143], v[58:59], v[130:131]
	global_store_dwordx4 v[140:141], v[172:175], off
	s_cbranch_vccnz .LBB0_622
	v_mul_f32_e32 v130, 0xbfb8aa3b, v136
	v_exp_f32_e32 v130, v130
	v_mul_f32_e32 v131, 0xbfb8aa3b, v137
	v_exp_f32_e32 v131, v131
	v_add_f32_e32 v130, 1.0, v130
	v_rcp_f32_e32 v136, v130
	v_mul_f32_e32 v130, 0xbfb8aa3b, v134
	v_add_f32_e32 v131, 1.0, v131
	v_exp_f32_e32 v130, v130
	v_mul_f32_e32 v134, 0xbfb8aa3b, v135
	v_exp_f32_e32 v135, v134
	v_rcp_f32_e32 v137, v131
	v_mul_f32_e32 v131, 0xbfb8aa3b, v142
	v_exp_f32_e32 v131, v131
	v_add_f32_e32 v130, 1.0, v130
	v_rcp_f32_e32 v134, v130
	v_add_f32_e32 v130, 1.0, v135
	v_mul_f32_e32 v135, 0xbfb8aa3b, v143
	v_exp_f32_e32 v143, v135
	v_rcp_f32_e32 v135, v130
	v_add_f32_e32 v130, 1.0, v131
	v_mul_f32_e32 v131, 0xbfb8aa3b, v132
	v_exp_f32_e32 v131, v131
	v_mul_f32_e32 v132, 0xbfb8aa3b, v133
	v_exp_f32_e32 v133, v132
	v_rcp_f32_e32 v142, v130
	v_add_f32_e32 v130, 1.0, v143
	v_rcp_f32_e32 v143, v130
	v_add_f32_e32 v130, 1.0, v131
	v_rcp_f32_e32 v132, v130
	v_add_f32_e32 v130, 1.0, v133
	v_rcp_f32_e32 v133, v130
.LBB0_622:
	v_cvt_f32_i32_e32 v129, v129
	v_cvt_f32_i32_e32 v128, v128
	s_nop 0
	v_cvt_pk_bf16_f32 v170, v136, v137
	s_nop 0
	v_cvt_pk_bf16_f32 v171, v134, v135
	s_nop 0
	v_cvt_pk_bf16_f32 v172, v142, v143
	v_cvt_f32_i32_e32 v127, v127
	v_cvt_f32_i32_e32 v126, v126
	s_nop 0
	v_cvt_pk_bf16_f32 v173, v132, v133
	v_cvt_f32_i32_e32 v133, v125
	v_cvt_f32_i32_e32 v123, v123
	v_cvt_f32_i32_e32 v122, v122
	v_cvt_f32_i32_e32 v132, v124
	v_mul_f32_e32 v130, v192, v193
	v_pk_mul_f32 v[128:129], v[130:131], v[128:129] op_sel_hi:[0,1]
	v_pk_mul_f32 v[126:127], v[130:131], v[126:127] op_sel_hi:[0,1]
	v_pk_mul_f32 v[124:125], v[80:81], v[128:129]
	v_pk_mul_f32 v[122:123], v[130:131], v[122:123] op_sel_hi:[0,1]
	v_pk_mul_f32 v[128:129], v[130:131], v[132:133] op_sel_hi:[0,1]
	v_pk_mul_f32 v[126:127], v[78:79], v[126:127]
	v_pk_mul_f32 v[128:129], v[76:77], v[128:129]
	s_and_b64 vcc, exec, s[6:7]
	v_pk_mul_f32 v[132:133], v[74:75], v[122:123]
	global_store_dwordx4 v[140:141], v[170:173], off offset:1024
	s_cbranch_vccnz .LBB0_624
	v_mul_f32_e32 v122, 0xbfb8aa3b, v126
	v_exp_f32_e32 v122, v122
	v_mul_f32_e32 v123, 0xbfb8aa3b, v127
	v_exp_f32_e32 v123, v123
	v_add_f32_e32 v122, 1.0, v122
	v_rcp_f32_e32 v126, v122
	v_mul_f32_e32 v122, 0xbfb8aa3b, v124
	v_add_f32_e32 v123, 1.0, v123
	v_exp_f32_e32 v122, v122
	v_mul_f32_e32 v124, 0xbfb8aa3b, v125
	v_exp_f32_e32 v125, v124
	v_rcp_f32_e32 v127, v123
	v_mul_f32_e32 v123, 0xbfb8aa3b, v132
	v_exp_f32_e32 v123, v123
	v_add_f32_e32 v122, 1.0, v122
	v_rcp_f32_e32 v124, v122
	v_add_f32_e32 v122, 1.0, v125
	v_mul_f32_e32 v125, 0xbfb8aa3b, v133
	v_exp_f32_e32 v131, v125
	v_rcp_f32_e32 v125, v122
	v_add_f32_e32 v122, 1.0, v123
	v_mul_f32_e32 v123, 0xbfb8aa3b, v128
	v_exp_f32_e32 v123, v123
	v_mul_f32_e32 v128, 0xbfb8aa3b, v129
	v_exp_f32_e32 v129, v128
	v_rcp_f32_e32 v132, v122
	v_add_f32_e32 v122, 1.0, v131
	v_rcp_f32_e32 v133, v122
	v_add_f32_e32 v122, 1.0, v123
	v_rcp_f32_e32 v128, v122
	v_add_f32_e32 v122, 1.0, v129
	v_rcp_f32_e32 v129, v122
.LBB0_624:
	v_cvt_f32_i32_e32 v119, v119
	v_cvt_f32_i32_e32 v121, v121
	v_cvt_f32_i32_e32 v120, v120
	v_cvt_f32_i32_e32 v118, v118
	v_cvt_f32_i32_e32 v115, v115
	v_cvt_f32_i32_e32 v117, v117
	v_cvt_f32_i32_e32 v116, v116
	v_cvt_f32_i32_e32 v114, v114
	v_mul_lo_u32 v134, s3, v168
	v_mul_lo_u32 v135, s2, v169
	v_mad_u64_u32 v[122:123], s[30:31], s2, v168, 0
	v_mov_b32_e32 v131, v130
	v_add3_u32 v123, v123, v135, v134
	s_nop 0
	v_cvt_pk_bf16_f32 v134, v126, v127
	s_nop 0
	v_cvt_pk_bf16_f32 v135, v124, v125
	v_mov_b32_e32 v124, v130
	v_mov_b32_e32 v125, v130
	v_pk_mul_f32 v[120:121], v[124:125], v[120:121]
	v_pk_mul_f32 v[126:127], v[130:131], v[118:119]
	v_pk_mul_f32 v[116:117], v[124:125], v[116:117]
	v_pk_mul_f32 v[114:115], v[130:131], v[114:115]
	s_mov_b64 s[98:99], 0x800
	v_lshl_add_u64 v[122:123], v[248:249], 0, s[98:99]
	v_pk_mul_f32 v[118:119], v[64:65], v[120:121]
	v_pk_mul_f32 v[120:121], v[62:63], v[126:127]
	v_pk_mul_f32 v[116:117], v[60:61], v[116:117]
	s_and_b64 vcc, exec, s[6:7]
	v_pk_mul_f32 v[124:125], v[58:59], v[114:115]
	s_nop 0
	v_cvt_pk_bf16_f32 v136, v132, v133
	s_nop 0
	v_cvt_pk_bf16_f32 v137, v128, v129
	global_store_dwordx4 v[122:123], v[134:137], off
	s_cbranch_vccnz .LBB0_626
	v_mul_f32_e32 v114, 0xbfb8aa3b, v120
	v_exp_f32_e32 v114, v114
	v_mul_f32_e32 v115, 0xbfb8aa3b, v121
	v_exp_f32_e32 v115, v115
	v_add_f32_e32 v114, 1.0, v114
	v_rcp_f32_e32 v120, v114
	v_mul_f32_e32 v114, 0xbfb8aa3b, v118
	v_add_f32_e32 v115, 1.0, v115
	v_exp_f32_e32 v114, v114
	v_mul_f32_e32 v118, 0xbfb8aa3b, v119
	v_exp_f32_e32 v119, v118
	v_rcp_f32_e32 v121, v115
	v_mul_f32_e32 v115, 0xbfb8aa3b, v124
	v_exp_f32_e32 v115, v115
	v_add_f32_e32 v114, 1.0, v114
	v_rcp_f32_e32 v118, v114
	v_add_f32_e32 v114, 1.0, v119
	v_mul_f32_e32 v119, 0xbfb8aa3b, v125
	v_exp_f32_e32 v125, v119
	v_rcp_f32_e32 v119, v114
	v_add_f32_e32 v114, 1.0, v115
	v_mul_f32_e32 v115, 0xbfb8aa3b, v116
	v_exp_f32_e32 v115, v115
	v_mul_f32_e32 v116, 0xbfb8aa3b, v117
	v_exp_f32_e32 v117, v116
	v_rcp_f32_e32 v124, v114
	v_add_f32_e32 v114, 1.0, v125
	v_rcp_f32_e32 v125, v114
	v_add_f32_e32 v114, 1.0, v115
	v_rcp_f32_e32 v116, v114
	v_add_f32_e32 v114, 1.0, v117
	v_rcp_f32_e32 v117, v114
; __device__ __forceinline__ u32x4 pack8(const f32x4 v0, const f32x4 v1) { u32x4 w; w.x = cvt_pk_bf16(v0[0], v0[1]); w.y = cvt_pk_bf16(v0[2], v0[3]); w.z = cvt_pk_bf16(v1[0], v1[1]); w.w = cvt_pk_bf16(v1[2], v1[3]); return w; }
; __device__ __forceinline__ f32x4 sig4(const f32x4 v) { return (f32x4){sigmoidf_(v[0]), sigmoidf_(v[1]), sigmoidf_(v[2]), sigmoidf_(v[3])}; }
;     __device__ __forceinline__ void operator()(const i32x4 (&acc)[2][2][4][2], const Unit& uu, int wr, int wc, int fr, int fq) const {
;     ...
;         for (int ai = 0; ai < 2; ++ai)
; #pragma unroll
;             for (int m = 0; m < 4; ++m) { const int r = row0 + ai * HALF + m * 16; const float rs = rsv[ai][m]; bf16_t* rowp = base + (size_t)r * ldc + col0;
; #pragma unroll
;                 for (int bj = 0; bj < 2; ++bj) { f32x4 v0 = __builtin_convertvector(acc[ai][bj][m][0], f32x4) * rs * sv[bj][0], v1 = __builtin_convertvector(acc[ai][bj][m][1], f32x4) * rs * sv[bj][1];
;                     if (sg) { v0 = sig4(v0); v1 = sig4(v1); }
;                     *(u32x4*)(rowp + bj * HALF) = pack8(v0, v1); } }
.LBB0_626:
	v_cvt_f32_i32_e32 v113, v113
	v_cvt_f32_i32_e32 v112, v112
	s_nop 0
	v_cvt_pk_bf16_f32 v126, v120, v121
	s_nop 0
	v_cvt_pk_bf16_f32 v127, v118, v119
	s_nop 0
	v_cvt_pk_bf16_f32 v128, v124, v125
	v_cvt_f32_i32_e32 v111, v111
	v_cvt_f32_i32_e32 v110, v110
	s_nop 0
	v_cvt_pk_bf16_f32 v129, v116, v117
	v_cvt_f32_i32_e32 v117, v109
	v_cvt_f32_i32_e32 v107, v107
	v_cvt_f32_i32_e32 v106, v106
	v_cvt_f32_i32_e32 v116, v108
	v_mul_f32_e32 v114, v190, v191
	v_pk_mul_f32 v[112:113], v[114:115], v[112:113] op_sel_hi:[0,1]
	v_pk_mul_f32 v[110:111], v[114:115], v[110:111] op_sel_hi:[0,1]
	v_pk_mul_f32 v[108:109], v[80:81], v[112:113]
	v_pk_mul_f32 v[106:107], v[114:115], v[106:107] op_sel_hi:[0,1]
	v_pk_mul_f32 v[112:113], v[114:115], v[116:117] op_sel_hi:[0,1]
	v_pk_mul_f32 v[110:111], v[78:79], v[110:111]
	v_pk_mul_f32 v[112:113], v[76:77], v[112:113]
	s_and_b64 vcc, exec, s[6:7]
	v_pk_mul_f32 v[116:117], v[74:75], v[106:107]
	global_store_dwordx4 v[122:123], v[126:129], off offset:1024
	s_cbranch_vccnz .LBB0_628
	v_mul_f32_e32 v106, 0xbfb8aa3b, v110
	v_exp_f32_e32 v106, v106
	v_mul_f32_e32 v107, 0xbfb8aa3b, v111
	v_exp_f32_e32 v107, v107
	v_add_f32_e32 v106, 1.0, v106
	v_rcp_f32_e32 v110, v106
	v_mul_f32_e32 v106, 0xbfb8aa3b, v108
	v_add_f32_e32 v107, 1.0, v107
	v_exp_f32_e32 v106, v106
	v_mul_f32_e32 v108, 0xbfb8aa3b, v109
	v_exp_f32_e32 v109, v108
	v_rcp_f32_e32 v111, v107
	v_mul_f32_e32 v107, 0xbfb8aa3b, v116
	v_exp_f32_e32 v107, v107
	v_add_f32_e32 v106, 1.0, v106
	v_rcp_f32_e32 v108, v106
	v_add_f32_e32 v106, 1.0, v109
	v_mul_f32_e32 v109, 0xbfb8aa3b, v117
	v_exp_f32_e32 v115, v109
	v_rcp_f32_e32 v109, v106
	v_add_f32_e32 v106, 1.0, v107
	v_mul_f32_e32 v107, 0xbfb8aa3b, v112
	v_exp_f32_e32 v107, v107
	v_mul_f32_e32 v112, 0xbfb8aa3b, v113
	v_exp_f32_e32 v113, v112
	v_rcp_f32_e32 v116, v106
	v_add_f32_e32 v106, 1.0, v115
	v_rcp_f32_e32 v117, v106
	v_add_f32_e32 v106, 1.0, v107
	v_rcp_f32_e32 v112, v106
	v_add_f32_e32 v106, 1.0, v113
	v_rcp_f32_e32 v113, v106
.LBB0_628:
	v_cvt_f32_i32_e32 v103, v103
	v_cvt_f32_i32_e32 v105, v105
	v_cvt_f32_i32_e32 v104, v104
	v_cvt_f32_i32_e32 v102, v102
	v_cvt_f32_i32_e32 v99, v99
	v_cvt_f32_i32_e32 v101, v101
	v_cvt_f32_i32_e32 v100, v100
	v_cvt_f32_i32_e32 v98, v98
	v_mul_lo_u32 v118, s3, v166
	v_mul_lo_u32 v119, s2, v167
	v_mad_u64_u32 v[106:107], s[30:31], s2, v166, 0
	v_mov_b32_e32 v115, v114
	v_add3_u32 v107, v107, v119, v118
	s_nop 0
	v_cvt_pk_bf16_f32 v118, v110, v111
	s_nop 0
	v_cvt_pk_bf16_f32 v119, v108, v109
	v_mov_b32_e32 v108, v114
	v_mov_b32_e32 v109, v114
	v_pk_mul_f32 v[104:105], v[108:109], v[104:105]
	v_pk_mul_f32 v[110:111], v[114:115], v[102:103]
	v_pk_mul_f32 v[100:101], v[108:109], v[100:101]
	v_pk_mul_f32 v[98:99], v[114:115], v[98:99]
	s_mov_b64 s[98:99], 0x1000
	v_lshl_add_u64 v[106:107], v[248:249], 0, s[98:99]
	v_pk_mul_f32 v[102:103], v[64:65], v[104:105]
	v_pk_mul_f32 v[104:105], v[62:63], v[110:111]
	v_pk_mul_f32 v[100:101], v[60:61], v[100:101]
	s_and_b64 vcc, exec, s[6:7]
	v_pk_mul_f32 v[108:109], v[58:59], v[98:99]
	s_nop 0
	v_cvt_pk_bf16_f32 v120, v116, v117
	s_nop 0
	v_cvt_pk_bf16_f32 v121, v112, v113
	global_store_dwordx4 v[106:107], v[118:121], off
	s_cbranch_vccnz .LBB0_630
	v_mul_f32_e32 v98, 0xbfb8aa3b, v104
	v_exp_f32_e32 v98, v98
	v_mul_f32_e32 v99, 0xbfb8aa3b, v105
	v_exp_f32_e32 v99, v99
	v_add_f32_e32 v98, 1.0, v98
	v_rcp_f32_e32 v104, v98
	v_mul_f32_e32 v98, 0xbfb8aa3b, v102
	v_add_f32_e32 v99, 1.0, v99
	v_exp_f32_e32 v98, v98
	v_mul_f32_e32 v102, 0xbfb8aa3b, v103
	v_exp_f32_e32 v103, v102
	v_rcp_f32_e32 v105, v99
	v_mul_f32_e32 v99, 0xbfb8aa3b, v108
	v_exp_f32_e32 v99, v99
	v_add_f32_e32 v98, 1.0, v98
	v_rcp_f32_e32 v102, v98
	v_add_f32_e32 v98, 1.0, v103
	v_mul_f32_e32 v103, 0xbfb8aa3b, v109
	v_exp_f32_e32 v109, v103
	v_rcp_f32_e32 v103, v98
	v_add_f32_e32 v98, 1.0, v99
	v_mul_f32_e32 v99, 0xbfb8aa3b, v100
	v_exp_f32_e32 v99, v99
	v_mul_f32_e32 v100, 0xbfb8aa3b, v101
	v_exp_f32_e32 v101, v100
	v_rcp_f32_e32 v108, v98
	v_add_f32_e32 v98, 1.0, v109
	v_rcp_f32_e32 v109, v98
	v_add_f32_e32 v98, 1.0, v99
	v_rcp_f32_e32 v100, v98
	v_add_f32_e32 v98, 1.0, v101
	v_rcp_f32_e32 v101, v98
.LBB0_630:
	v_cvt_f32_i32_e32 v97, v97
	v_cvt_f32_i32_e32 v96, v96
	s_nop 0
	v_cvt_pk_bf16_f32 v110, v104, v105
	s_nop 0
	v_cvt_pk_bf16_f32 v111, v102, v103
	s_nop 0
	v_cvt_pk_bf16_f32 v112, v108, v109
	v_cvt_f32_i32_e32 v95, v95
	v_cvt_f32_i32_e32 v94, v94
	s_nop 0
	v_cvt_pk_bf16_f32 v113, v100, v101
	v_cvt_f32_i32_e32 v101, v93
	v_cvt_f32_i32_e32 v91, v91
	v_cvt_f32_i32_e32 v90, v90
	v_cvt_f32_i32_e32 v100, v92
	v_mul_f32_e32 v98, v188, v189
	v_pk_mul_f32 v[96:97], v[98:99], v[96:97] op_sel_hi:[0,1]
	v_pk_mul_f32 v[94:95], v[98:99], v[94:95] op_sel_hi:[0,1]
	v_pk_mul_f32 v[92:93], v[80:81], v[96:97]
	v_pk_mul_f32 v[90:91], v[98:99], v[90:91] op_sel_hi:[0,1]
	v_pk_mul_f32 v[96:97], v[98:99], v[100:101] op_sel_hi:[0,1]
	v_pk_mul_f32 v[94:95], v[78:79], v[94:95]
	v_pk_mul_f32 v[96:97], v[76:77], v[96:97]
	s_and_b64 vcc, exec, s[6:7]
	v_pk_mul_f32 v[100:101], v[74:75], v[90:91]
	global_store_dwordx4 v[106:107], v[110:113], off offset:1024
	s_cbranch_vccnz .LBB0_632
	v_mul_f32_e32 v90, 0xbfb8aa3b, v94
	v_exp_f32_e32 v90, v90
	v_mul_f32_e32 v91, 0xbfb8aa3b, v95
	v_exp_f32_e32 v91, v91
	v_add_f32_e32 v90, 1.0, v90
	v_rcp_f32_e32 v94, v90
	v_mul_f32_e32 v90, 0xbfb8aa3b, v92
	v_add_f32_e32 v91, 1.0, v91
	v_exp_f32_e32 v90, v90
	v_mul_f32_e32 v92, 0xbfb8aa3b, v93
	v_exp_f32_e32 v93, v92
	v_rcp_f32_e32 v95, v91
	v_mul_f32_e32 v91, 0xbfb8aa3b, v100
	v_exp_f32_e32 v91, v91
	v_add_f32_e32 v90, 1.0, v90
	v_rcp_f32_e32 v92, v90
	v_add_f32_e32 v90, 1.0, v93
	v_mul_f32_e32 v93, 0xbfb8aa3b, v101
	v_exp_f32_e32 v99, v93
	v_rcp_f32_e32 v93, v90
	v_add_f32_e32 v90, 1.0, v91
	v_mul_f32_e32 v91, 0xbfb8aa3b, v96
	v_exp_f32_e32 v91, v91
	v_mul_f32_e32 v96, 0xbfb8aa3b, v97
	v_exp_f32_e32 v97, v96
	v_rcp_f32_e32 v100, v90
	v_add_f32_e32 v90, 1.0, v99
	v_rcp_f32_e32 v101, v90
	v_add_f32_e32 v90, 1.0, v91
	v_rcp_f32_e32 v96, v90
	v_add_f32_e32 v90, 1.0, v97
	v_rcp_f32_e32 v97, v90
; __device__ __forceinline__ u32x4 pack8(const f32x4 v0, const f32x4 v1) { u32x4 w; w.x = cvt_pk_bf16(v0[0], v0[1]); w.y = cvt_pk_bf16(v0[2], v0[3]); w.z = cvt_pk_bf16(v1[0], v1[1]); w.w = cvt_pk_bf16(v1[2], v1[3]); return w; }
; __device__ __forceinline__ f32x4 sig4(const f32x4 v) { return (f32x4){sigmoidf_(v[0]), sigmoidf_(v[1]), sigmoidf_(v[2]), sigmoidf_(v[3])}; }
;     __device__ __forceinline__ void operator()(const i32x4 (&acc)[2][2][4][2], const Unit& uu, int wr, int wc, int fr, int fq) const {
;     ...
;         for (int ai = 0; ai < 2; ++ai)
; #pragma unroll
;             for (int m = 0; m < 4; ++m) { const int r = row0 + ai * HALF + m * 16; const float rs = rsv[ai][m]; bf16_t* rowp = base + (size_t)r * ldc + col0;
; #pragma unroll
;                 for (int bj = 0; bj < 2; ++bj) { f32x4 v0 = __builtin_convertvector(acc[ai][bj][m][0], f32x4) * rs * sv[bj][0], v1 = __builtin_convertvector(acc[ai][bj][m][1], f32x4) * rs * sv[bj][1];
;                     if (sg) { v0 = sig4(v0); v1 = sig4(v1); }
;                     *(u32x4*)(rowp + bj * HALF) = pack8(v0, v1); } }
.LBB0_632:
	v_cvt_f32_i32_e32 v87, v87
	v_cvt_f32_i32_e32 v89, v89
	v_cvt_f32_i32_e32 v88, v88
	v_cvt_f32_i32_e32 v86, v86
	v_cvt_f32_i32_e32 v83, v83
	v_cvt_f32_i32_e32 v85, v85
	v_cvt_f32_i32_e32 v84, v84
	v_cvt_f32_i32_e32 v82, v82
	v_mul_lo_u32 v102, s3, v164
	v_mul_lo_u32 v103, s2, v165
	v_mad_u64_u32 v[90:91], s[30:31], s2, v164, 0
	v_mov_b32_e32 v99, v98
	v_add3_u32 v91, v91, v103, v102
	s_nop 0
	v_cvt_pk_bf16_f32 v102, v94, v95
	s_nop 0
	v_cvt_pk_bf16_f32 v103, v92, v93
	v_mov_b32_e32 v92, v98
	v_mov_b32_e32 v93, v98
	v_pk_mul_f32 v[88:89], v[92:93], v[88:89]
	v_pk_mul_f32 v[94:95], v[98:99], v[86:87]
	v_pk_mul_f32 v[84:85], v[92:93], v[84:85]
	v_pk_mul_f32 v[82:83], v[98:99], v[82:83]
	s_mov_b64 s[98:99], 0x1800
	v_lshl_add_u64 v[90:91], v[248:249], 0, s[98:99]
	v_pk_mul_f32 v[86:87], v[64:65], v[88:89]
	v_pk_mul_f32 v[88:89], v[62:63], v[94:95]
	v_pk_mul_f32 v[84:85], v[60:61], v[84:85]
	s_and_b64 vcc, exec, s[6:7]
	v_pk_mul_f32 v[92:93], v[58:59], v[82:83]
	s_nop 0
	v_cvt_pk_bf16_f32 v104, v100, v101
	s_nop 0
	v_cvt_pk_bf16_f32 v105, v96, v97
	global_store_dwordx4 v[90:91], v[102:105], off
	s_cbranch_vccnz .LBB0_634
	v_mul_f32_e32 v82, 0xbfb8aa3b, v88
	v_exp_f32_e32 v82, v82
	v_mul_f32_e32 v83, 0xbfb8aa3b, v89
	v_exp_f32_e32 v83, v83
	v_add_f32_e32 v82, 1.0, v82
	v_rcp_f32_e32 v88, v82
	v_mul_f32_e32 v82, 0xbfb8aa3b, v86
	v_add_f32_e32 v83, 1.0, v83
	v_exp_f32_e32 v82, v82
	v_mul_f32_e32 v86, 0xbfb8aa3b, v87
	v_exp_f32_e32 v87, v86
	v_rcp_f32_e32 v89, v83
	v_mul_f32_e32 v83, 0xbfb8aa3b, v92
	v_exp_f32_e32 v83, v83
	v_add_f32_e32 v82, 1.0, v82
	v_rcp_f32_e32 v86, v82
	v_add_f32_e32 v82, 1.0, v87
	v_mul_f32_e32 v87, 0xbfb8aa3b, v93
	v_exp_f32_e32 v93, v87
	v_rcp_f32_e32 v87, v82
	v_add_f32_e32 v82, 1.0, v83
	v_mul_f32_e32 v83, 0xbfb8aa3b, v84
	v_exp_f32_e32 v83, v83
	v_mul_f32_e32 v84, 0xbfb8aa3b, v85
	v_exp_f32_e32 v85, v84
	v_rcp_f32_e32 v92, v82
	v_add_f32_e32 v82, 1.0, v93
	v_rcp_f32_e32 v93, v82
	v_add_f32_e32 v82, 1.0, v83
	v_rcp_f32_e32 v84, v82
	v_add_f32_e32 v82, 1.0, v85
	v_rcp_f32_e32 v85, v82
.LBB0_634:
	v_cvt_f32_i32_e32 v73, v73
	v_cvt_f32_i32_e32 v72, v72
	s_nop 0
	v_cvt_pk_bf16_f32 v94, v88, v89
	s_nop 0
	v_cvt_pk_bf16_f32 v95, v86, v87
	s_nop 0
	v_cvt_pk_bf16_f32 v96, v92, v93
	v_cvt_f32_i32_e32 v71, v71
	v_cvt_f32_i32_e32 v70, v70
	s_nop 0
	v_cvt_pk_bf16_f32 v97, v84, v85
	v_cvt_f32_i32_e32 v85, v69
	v_cvt_f32_i32_e32 v67, v67
	v_cvt_f32_i32_e32 v66, v66
	v_cvt_f32_i32_e32 v84, v68
	v_mul_f32_e32 v82, v186, v187
	v_pk_mul_f32 v[72:73], v[82:83], v[72:73] op_sel_hi:[0,1]
	v_pk_mul_f32 v[70:71], v[82:83], v[70:71] op_sel_hi:[0,1]
	v_pk_mul_f32 v[68:69], v[80:81], v[72:73]
	v_pk_mul_f32 v[66:67], v[82:83], v[66:67] op_sel_hi:[0,1]
	v_pk_mul_f32 v[72:73], v[82:83], v[84:85] op_sel_hi:[0,1]
	v_pk_mul_f32 v[70:71], v[78:79], v[70:71]
	v_pk_mul_f32 v[72:73], v[76:77], v[72:73]
	s_and_b64 vcc, exec, s[6:7]
	v_pk_mul_f32 v[84:85], v[74:75], v[66:67]
	global_store_dwordx4 v[90:91], v[94:97], off offset:1024
	s_cbranch_vccnz .LBB0_636
	v_mul_f32_e32 v66, 0xbfb8aa3b, v70
	v_exp_f32_e32 v66, v66
	v_mul_f32_e32 v67, 0xbfb8aa3b, v71
	v_exp_f32_e32 v67, v67
	v_add_f32_e32 v66, 1.0, v66
	v_rcp_f32_e32 v70, v66
	v_mul_f32_e32 v66, 0xbfb8aa3b, v68
	v_add_f32_e32 v67, 1.0, v67
	v_exp_f32_e32 v66, v66
	v_mul_f32_e32 v68, 0xbfb8aa3b, v69
	v_exp_f32_e32 v69, v68
	v_rcp_f32_e32 v71, v67
	v_mul_f32_e32 v67, 0xbfb8aa3b, v84
	v_exp_f32_e32 v67, v67
	v_add_f32_e32 v66, 1.0, v66
	v_rcp_f32_e32 v68, v66
	v_add_f32_e32 v66, 1.0, v69
	v_mul_f32_e32 v69, 0xbfb8aa3b, v85
	v_exp_f32_e32 v83, v69
	v_rcp_f32_e32 v69, v66
	v_add_f32_e32 v66, 1.0, v67
	v_mul_f32_e32 v67, 0xbfb8aa3b, v72
	v_exp_f32_e32 v67, v67
	v_mul_f32_e32 v72, 0xbfb8aa3b, v73
	v_exp_f32_e32 v73, v72
	v_rcp_f32_e32 v84, v66
	v_add_f32_e32 v66, 1.0, v83
	v_rcp_f32_e32 v85, v66
	v_add_f32_e32 v66, 1.0, v67
	v_rcp_f32_e32 v72, v66
	v_add_f32_e32 v66, 1.0, v73
	v_rcp_f32_e32 v73, v66
.LBB0_636:
	v_add_u32_e32 v66, 0x80, v162
	v_cvt_f32_i32_e32 v55, v55
	v_cvt_f32_i32_e32 v57, v57
	v_cvt_f32_i32_e32 v56, v56
	v_cvt_f32_i32_e32 v54, v54
	v_cvt_f32_i32_e32 v51, v51
	v_cvt_f32_i32_e32 v53, v53
	v_cvt_f32_i32_e32 v52, v52
	v_cvt_f32_i32_e32 v50, v50
	v_ashrrev_i32_e32 v67, 31, v66
	v_mul_lo_u32 v86, s2, v67
	v_mul_lo_u32 v87, s3, v66
	v_mad_u64_u32 v[66:67], s[30:31], s2, v66, 0
	v_mov_b32_e32 v83, v82
	v_add3_u32 v67, v67, v86, v87
	s_nop 0
	v_cvt_pk_bf16_f32 v86, v70, v71
	s_nop 0
	v_cvt_pk_bf16_f32 v87, v68, v69
	v_mov_b32_e32 v68, v82
	v_mov_b32_e32 v69, v82
	v_pk_mul_f32 v[56:57], v[68:69], v[56:57]
	v_pk_mul_f32 v[70:71], v[82:83], v[54:55]
	v_pk_mul_f32 v[52:53], v[68:69], v[52:53]
	v_pk_mul_f32 v[50:51], v[82:83], v[50:51]
	s_mov_b64 s[98:99], 0x2000
	v_lshl_add_u64 v[66:67], v[248:249], 0, s[98:99]
	v_pk_mul_f32 v[54:55], v[64:65], v[56:57]
	v_pk_mul_f32 v[56:57], v[62:63], v[70:71]
	v_pk_mul_f32 v[52:53], v[60:61], v[52:53]
	s_and_b64 vcc, exec, s[6:7]
	v_pk_mul_f32 v[68:69], v[58:59], v[50:51]
	s_nop 0
	v_cvt_pk_bf16_f32 v88, v84, v85
	s_nop 0
	v_cvt_pk_bf16_f32 v89, v72, v73
	global_store_dwordx4 v[66:67], v[86:89], off
	s_cbranch_vccnz .LBB0_638
	v_mul_f32_e32 v50, 0xbfb8aa3b, v56
	v_exp_f32_e32 v50, v50
	v_mul_f32_e32 v51, 0xbfb8aa3b, v57
	v_exp_f32_e32 v51, v51
	v_add_f32_e32 v50, 1.0, v50
	v_rcp_f32_e32 v56, v50
	v_mul_f32_e32 v50, 0xbfb8aa3b, v54
	v_add_f32_e32 v51, 1.0, v51
	v_exp_f32_e32 v50, v50
	v_mul_f32_e32 v54, 0xbfb8aa3b, v55
	v_exp_f32_e32 v55, v54
	v_rcp_f32_e32 v57, v51
	v_mul_f32_e32 v51, 0xbfb8aa3b, v68
	v_exp_f32_e32 v51, v51
	v_add_f32_e32 v50, 1.0, v50
	v_rcp_f32_e32 v54, v50
	v_add_f32_e32 v50, 1.0, v55
	v_mul_f32_e32 v55, 0xbfb8aa3b, v69
	v_exp_f32_e32 v69, v55
	v_rcp_f32_e32 v55, v50
	v_add_f32_e32 v50, 1.0, v51
	v_mul_f32_e32 v51, 0xbfb8aa3b, v52
	v_exp_f32_e32 v51, v51
	v_mul_f32_e32 v52, 0xbfb8aa3b, v53
	v_exp_f32_e32 v53, v52
	v_rcp_f32_e32 v68, v50
	v_add_f32_e32 v50, 1.0, v69
	v_rcp_f32_e32 v69, v50
	v_add_f32_e32 v50, 1.0, v51
	v_rcp_f32_e32 v52, v50
	v_add_f32_e32 v50, 1.0, v53
	v_rcp_f32_e32 v53, v50
; __device__ __forceinline__ unsigned cvt_pk_bf16(float lo, float hi) { unsigned r; asm volatile("s_nop 0\n\tv_cvt_pk_bf16_f32 %0, %1, %2" : "=v"(r) : "v"(lo), "v"(hi)); return r; }
; __device__ __forceinline__ float sigmoidf_(float x) { return __builtin_amdgcn_rcpf(1.0f + __builtin_amdgcn_exp2f(-1.4426950408889634f * x)); }
; __device__ __forceinline__ u32x4 pack8(const f32x4 v0, const f32x4 v1) { u32x4 w; w.x = cvt_pk_bf16(v0[0], v0[1]); w.y = cvt_pk_bf16(v0[2], v0[3]); w.z = cvt_pk_bf16(v1[0], v1[1]); w.w = cvt_pk_bf16(v1[2], v1[3]); return w; }
; __device__ __forceinline__ void unpack8(const u32x4 w, f32x4& v0, f32x4& v1) { v0 = (f32x4){bf_lo(w.x), bf_hi(w.x), bf_lo(w.y), bf_hi(w.y)}; v1 = (f32x4){bf_lo(w.z), bf_hi(w.z), bf_lo(w.w), bf_hi(w.w)}; }
; __device__ __forceinline__ f32x4 sig4(const f32x4 v) { return (f32x4){sigmoidf_(v[0]), sigmoidf_(v[1]), sigmoidf_(v[2]), sigmoidf_(v[3])}; }
;     __device__ __forceinline__ void operator()(const i32x4 (&acc)[2][2][4][2], const Unit& uu, int wr, int wc, int fr, int fq) const {
;     ...
;         for (int ai = 0; ai < 2; ++ai)
; #pragma unroll
;             for (int m = 0; m < 4; ++m) { const int r = row0 + ai * HALF + m * 16; const float rs = rsv[ai][m]; bf16_t* rowp = base + (size_t)r * ldc + col0;
; #pragma unroll
;                 for (int bj = 0; bj < 2; ++bj) { f32x4 v0 = __builtin_convertvector(acc[ai][bj][m][0], f32x4) * rs * sv[bj][0], v1 = __builtin_convertvector(acc[ai][bj][m][1], f32x4) * rs * sv[bj][1];
;                     if (sg) { v0 = sig4(v0); v1 = sig4(v1); }
;                     *(u32x4*)(rowp + bj * HALF) = pack8(v0, v1); } }
.LBB0_638:
	v_cvt_f32_i32_e32 v49, v49
	v_cvt_f32_i32_e32 v48, v48
	s_nop 0
	v_cvt_pk_bf16_f32 v70, v56, v57
	s_nop 0
	v_cvt_pk_bf16_f32 v71, v54, v55
	s_nop 0
	v_cvt_pk_bf16_f32 v72, v68, v69
	v_cvt_f32_i32_e32 v47, v47
	v_cvt_f32_i32_e32 v46, v46
	s_nop 0
	v_cvt_pk_bf16_f32 v73, v52, v53
	v_cvt_f32_i32_e32 v53, v45
	v_cvt_f32_i32_e32 v43, v43
	v_cvt_f32_i32_e32 v42, v42
	v_cvt_f32_i32_e32 v52, v44
	v_mul_f32_e32 v50, v184, v185
	v_pk_mul_f32 v[48:49], v[50:51], v[48:49] op_sel_hi:[0,1]
	v_pk_mul_f32 v[46:47], v[50:51], v[46:47] op_sel_hi:[0,1]
	v_pk_mul_f32 v[44:45], v[80:81], v[48:49]
	v_pk_mul_f32 v[42:43], v[50:51], v[42:43] op_sel_hi:[0,1]
	v_pk_mul_f32 v[48:49], v[50:51], v[52:53] op_sel_hi:[0,1]
	v_pk_mul_f32 v[46:47], v[78:79], v[46:47]
	v_pk_mul_f32 v[48:49], v[76:77], v[48:49]
	s_and_b64 vcc, exec, s[6:7]
	v_pk_mul_f32 v[52:53], v[74:75], v[42:43]
	global_store_dwordx4 v[66:67], v[70:73], off offset:1024
	s_cbranch_vccnz .LBB0_640
	v_mul_f32_e32 v42, 0xbfb8aa3b, v46
	v_exp_f32_e32 v42, v42
	v_mul_f32_e32 v43, 0xbfb8aa3b, v47
	v_exp_f32_e32 v43, v43
	v_add_f32_e32 v42, 1.0, v42
	v_rcp_f32_e32 v46, v42
	v_mul_f32_e32 v42, 0xbfb8aa3b, v44
	v_add_f32_e32 v43, 1.0, v43
	v_exp_f32_e32 v42, v42
	v_mul_f32_e32 v44, 0xbfb8aa3b, v45
	v_exp_f32_e32 v45, v44
	v_rcp_f32_e32 v47, v43
	v_mul_f32_e32 v43, 0xbfb8aa3b, v52
	v_exp_f32_e32 v43, v43
	v_add_f32_e32 v42, 1.0, v42
	v_rcp_f32_e32 v44, v42
	v_add_f32_e32 v42, 1.0, v45
	v_mul_f32_e32 v45, 0xbfb8aa3b, v53
	v_exp_f32_e32 v51, v45
	v_rcp_f32_e32 v45, v42
	v_add_f32_e32 v42, 1.0, v43
	v_mul_f32_e32 v43, 0xbfb8aa3b, v48
	v_exp_f32_e32 v43, v43
	v_mul_f32_e32 v48, 0xbfb8aa3b, v49
	v_exp_f32_e32 v49, v48
	v_rcp_f32_e32 v52, v42
	v_add_f32_e32 v42, 1.0, v51
	v_rcp_f32_e32 v53, v42
	v_add_f32_e32 v42, 1.0, v43
	v_rcp_f32_e32 v48, v42
	v_add_f32_e32 v42, 1.0, v49
	v_rcp_f32_e32 v49, v42
.LBB0_640:
	v_add_u32_e32 v42, 0x90, v162
	v_cvt_f32_i32_e32 v39, v39
	v_cvt_f32_i32_e32 v41, v41
	v_cvt_f32_i32_e32 v40, v40
	v_cvt_f32_i32_e32 v38, v38
	v_cvt_f32_i32_e32 v35, v35
	v_cvt_f32_i32_e32 v37, v37
	v_cvt_f32_i32_e32 v36, v36
	v_cvt_f32_i32_e32 v34, v34
	v_ashrrev_i32_e32 v43, 31, v42
	v_mul_lo_u32 v54, s2, v43
	v_mul_lo_u32 v55, s3, v42
	v_mad_u64_u32 v[42:43], s[30:31], s2, v42, 0
	v_mov_b32_e32 v51, v50
	v_add3_u32 v43, v43, v54, v55
	s_nop 0
	v_cvt_pk_bf16_f32 v54, v46, v47
	s_nop 0
	v_cvt_pk_bf16_f32 v55, v44, v45
	v_mov_b32_e32 v44, v50
	v_mov_b32_e32 v45, v50
	v_pk_mul_f32 v[40:41], v[44:45], v[40:41]
	v_pk_mul_f32 v[46:47], v[50:51], v[38:39]
	v_pk_mul_f32 v[36:37], v[44:45], v[36:37]
	v_pk_mul_f32 v[34:35], v[50:51], v[34:35]
	s_mov_b64 s[98:99], 0x2800
	v_lshl_add_u64 v[42:43], v[248:249], 0, s[98:99]
	v_pk_mul_f32 v[38:39], v[64:65], v[40:41]
	v_pk_mul_f32 v[40:41], v[62:63], v[46:47]
	v_pk_mul_f32 v[36:37], v[60:61], v[36:37]
	s_and_b64 vcc, exec, s[6:7]
	v_pk_mul_f32 v[44:45], v[58:59], v[34:35]
	s_nop 0
	v_cvt_pk_bf16_f32 v56, v52, v53
	s_nop 0
	v_cvt_pk_bf16_f32 v57, v48, v49
	global_store_dwordx4 v[42:43], v[54:57], off
	s_cbranch_vccnz .LBB0_642
	v_mul_f32_e32 v34, 0xbfb8aa3b, v40
	v_exp_f32_e32 v34, v34
	v_mul_f32_e32 v35, 0xbfb8aa3b, v41
	v_exp_f32_e32 v35, v35
	v_add_f32_e32 v34, 1.0, v34
	v_rcp_f32_e32 v40, v34
	v_mul_f32_e32 v34, 0xbfb8aa3b, v38
	v_add_f32_e32 v35, 1.0, v35
	v_exp_f32_e32 v34, v34
	v_mul_f32_e32 v38, 0xbfb8aa3b, v39
	v_exp_f32_e32 v39, v38
	v_rcp_f32_e32 v41, v35
	v_mul_f32_e32 v35, 0xbfb8aa3b, v44
	v_exp_f32_e32 v35, v35
	v_add_f32_e32 v34, 1.0, v34
	v_rcp_f32_e32 v38, v34
	v_add_f32_e32 v34, 1.0, v39
	v_mul_f32_e32 v39, 0xbfb8aa3b, v45
	v_exp_f32_e32 v45, v39
	v_rcp_f32_e32 v39, v34
	v_add_f32_e32 v34, 1.0, v35
	v_mul_f32_e32 v35, 0xbfb8aa3b, v36
	v_exp_f32_e32 v35, v35
	v_mul_f32_e32 v36, 0xbfb8aa3b, v37
	v_exp_f32_e32 v37, v36
	v_rcp_f32_e32 v44, v34
	v_add_f32_e32 v34, 1.0, v45
	v_rcp_f32_e32 v45, v34
	v_add_f32_e32 v34, 1.0, v35
	v_rcp_f32_e32 v36, v34
	v_add_f32_e32 v34, 1.0, v37
	v_rcp_f32_e32 v37, v34
.LBB0_642:
	v_cvt_f32_i32_e32 v33, v33
	v_cvt_f32_i32_e32 v32, v32
	s_nop 0
	v_cvt_pk_bf16_f32 v46, v40, v41
	s_nop 0
	v_cvt_pk_bf16_f32 v47, v38, v39
	s_nop 0
	v_cvt_pk_bf16_f32 v48, v44, v45
	v_cvt_f32_i32_e32 v31, v31
	v_cvt_f32_i32_e32 v30, v30
	s_nop 0
	v_cvt_pk_bf16_f32 v49, v36, v37
	v_cvt_f32_i32_e32 v37, v29
	v_cvt_f32_i32_e32 v27, v27
	v_cvt_f32_i32_e32 v26, v26
	v_cvt_f32_i32_e32 v36, v28
	v_mul_f32_e32 v34, v182, v183
	v_pk_mul_f32 v[32:33], v[34:35], v[32:33] op_sel_hi:[0,1]
	v_pk_mul_f32 v[30:31], v[34:35], v[30:31] op_sel_hi:[0,1]
	v_pk_mul_f32 v[28:29], v[80:81], v[32:33]
	v_pk_mul_f32 v[26:27], v[34:35], v[26:27] op_sel_hi:[0,1]
	v_pk_mul_f32 v[32:33], v[34:35], v[36:37] op_sel_hi:[0,1]
	v_pk_mul_f32 v[30:31], v[78:79], v[30:31]
	v_pk_mul_f32 v[32:33], v[76:77], v[32:33]
	s_and_b64 vcc, exec, s[6:7]
	v_pk_mul_f32 v[36:37], v[74:75], v[26:27]
	global_store_dwordx4 v[42:43], v[46:49], off offset:1024
	s_cbranch_vccnz .LBB0_644
	v_mul_f32_e32 v26, 0xbfb8aa3b, v30
	v_exp_f32_e32 v26, v26
	v_mul_f32_e32 v27, 0xbfb8aa3b, v31
	v_exp_f32_e32 v27, v27
	v_add_f32_e32 v26, 1.0, v26
	v_rcp_f32_e32 v30, v26
	v_mul_f32_e32 v26, 0xbfb8aa3b, v28
	v_add_f32_e32 v27, 1.0, v27
	v_exp_f32_e32 v26, v26
	v_mul_f32_e32 v28, 0xbfb8aa3b, v29
	v_exp_f32_e32 v29, v28
	v_rcp_f32_e32 v31, v27
	v_mul_f32_e32 v27, 0xbfb8aa3b, v36
	v_exp_f32_e32 v27, v27
	v_add_f32_e32 v26, 1.0, v26
	v_rcp_f32_e32 v28, v26
	v_add_f32_e32 v26, 1.0, v29
	v_mul_f32_e32 v29, 0xbfb8aa3b, v37
	v_exp_f32_e32 v35, v29
	v_rcp_f32_e32 v29, v26
	v_add_f32_e32 v26, 1.0, v27
	v_mul_f32_e32 v27, 0xbfb8aa3b, v32
	v_exp_f32_e32 v27, v27
	v_mul_f32_e32 v32, 0xbfb8aa3b, v33
	v_exp_f32_e32 v33, v32
	v_rcp_f32_e32 v36, v26
	v_add_f32_e32 v26, 1.0, v35
	v_rcp_f32_e32 v37, v26
	v_add_f32_e32 v26, 1.0, v27
	v_rcp_f32_e32 v32, v26
	v_add_f32_e32 v26, 1.0, v33
	v_rcp_f32_e32 v33, v26
; __device__ __forceinline__ unsigned cvt_pk_bf16(float lo, float hi) { unsigned r; asm volatile("s_nop 0\n\tv_cvt_pk_bf16_f32 %0, %1, %2" : "=v"(r) : "v"(lo), "v"(hi)); return r; }
; __device__ __forceinline__ float sigmoidf_(float x) { return __builtin_amdgcn_rcpf(1.0f + __builtin_amdgcn_exp2f(-1.4426950408889634f * x)); }
; __device__ __forceinline__ u32x4 pack8(const f32x4 v0, const f32x4 v1) { u32x4 w; w.x = cvt_pk_bf16(v0[0], v0[1]); w.y = cvt_pk_bf16(v0[2], v0[3]); w.z = cvt_pk_bf16(v1[0], v1[1]); w.w = cvt_pk_bf16(v1[2], v1[3]); return w; }
; __device__ __forceinline__ void unpack8(const u32x4 w, f32x4& v0, f32x4& v1) { v0 = (f32x4){bf_lo(w.x), bf_hi(w.x), bf_lo(w.y), bf_hi(w.y)}; v1 = (f32x4){bf_lo(w.z), bf_hi(w.z), bf_lo(w.w), bf_hi(w.w)}; }
; __device__ __forceinline__ f32x4 sig4(const f32x4 v) { return (f32x4){sigmoidf_(v[0]), sigmoidf_(v[1]), sigmoidf_(v[2]), sigmoidf_(v[3])}; }
;     __device__ __forceinline__ void operator()(const i32x4 (&acc)[2][2][4][2], const Unit& uu, int wr, int wc, int fr, int fq) const {
;     ...
;         for (int ai = 0; ai < 2; ++ai)
; #pragma unroll
;             for (int m = 0; m < 4; ++m) { const int r = row0 + ai * HALF + m * 16; const float rs = rsv[ai][m]; bf16_t* rowp = base + (size_t)r * ldc + col0;
; #pragma unroll
;                 for (int bj = 0; bj < 2; ++bj) { f32x4 v0 = __builtin_convertvector(acc[ai][bj][m][0], f32x4) * rs * sv[bj][0], v1 = __builtin_convertvector(acc[ai][bj][m][1], f32x4) * rs * sv[bj][1];
;                     if (sg) { v0 = sig4(v0); v1 = sig4(v1); }
;                     *(u32x4*)(rowp + bj * HALF) = pack8(v0, v1); } }
.LBB0_644:
	v_add_u32_e32 v26, 0xa0, v162
	v_cvt_f32_i32_e32 v23, v23
	v_cvt_f32_i32_e32 v25, v25
	v_cvt_f32_i32_e32 v24, v24
	v_cvt_f32_i32_e32 v22, v22
	v_cvt_f32_i32_e32 v19, v19
	v_cvt_f32_i32_e32 v21, v21
	v_cvt_f32_i32_e32 v20, v20
	v_cvt_f32_i32_e32 v18, v18
	v_ashrrev_i32_e32 v27, 31, v26
	v_mul_lo_u32 v38, s2, v27
	v_mul_lo_u32 v39, s3, v26
	v_mad_u64_u32 v[26:27], s[30:31], s2, v26, 0
	v_mov_b32_e32 v35, v34
	v_add3_u32 v27, v27, v38, v39
	s_nop 0
	v_cvt_pk_bf16_f32 v38, v30, v31
	s_nop 0
	v_cvt_pk_bf16_f32 v39, v28, v29
	v_mov_b32_e32 v28, v34
	v_mov_b32_e32 v29, v34
	v_pk_mul_f32 v[24:25], v[28:29], v[24:25]
	v_pk_mul_f32 v[30:31], v[34:35], v[22:23]
	v_pk_mul_f32 v[20:21], v[28:29], v[20:21]
	v_pk_mul_f32 v[18:19], v[34:35], v[18:19]
	s_mov_b64 s[98:99], 0x3000
	v_lshl_add_u64 v[26:27], v[248:249], 0, s[98:99]
	v_pk_mul_f32 v[22:23], v[64:65], v[24:25]
	v_pk_mul_f32 v[24:25], v[62:63], v[30:31]
	v_pk_mul_f32 v[20:21], v[60:61], v[20:21]
	s_and_b64 vcc, exec, s[6:7]
	v_pk_mul_f32 v[28:29], v[58:59], v[18:19]
	s_nop 0
	v_cvt_pk_bf16_f32 v40, v36, v37
	s_nop 0
	v_cvt_pk_bf16_f32 v41, v32, v33
	global_store_dwordx4 v[26:27], v[38:41], off
	s_cbranch_vccnz .LBB0_646
	v_mul_f32_e32 v18, 0xbfb8aa3b, v24
	v_exp_f32_e32 v18, v18
	v_mul_f32_e32 v19, 0xbfb8aa3b, v25
	v_exp_f32_e32 v19, v19
	v_add_f32_e32 v18, 1.0, v18
	v_rcp_f32_e32 v24, v18
	v_mul_f32_e32 v18, 0xbfb8aa3b, v22
	v_add_f32_e32 v19, 1.0, v19
	v_exp_f32_e32 v18, v18
	v_mul_f32_e32 v22, 0xbfb8aa3b, v23
	v_exp_f32_e32 v23, v22
	v_rcp_f32_e32 v25, v19
	v_mul_f32_e32 v19, 0xbfb8aa3b, v28
	v_exp_f32_e32 v19, v19
	v_add_f32_e32 v18, 1.0, v18
	v_rcp_f32_e32 v22, v18
	v_add_f32_e32 v18, 1.0, v23
	v_mul_f32_e32 v23, 0xbfb8aa3b, v29
	v_exp_f32_e32 v29, v23
	v_rcp_f32_e32 v23, v18
	v_add_f32_e32 v18, 1.0, v19
	v_mul_f32_e32 v19, 0xbfb8aa3b, v20
	v_exp_f32_e32 v19, v19
	v_mul_f32_e32 v20, 0xbfb8aa3b, v21
	v_exp_f32_e32 v21, v20
	v_rcp_f32_e32 v28, v18
	v_add_f32_e32 v18, 1.0, v29
	v_rcp_f32_e32 v29, v18
	v_add_f32_e32 v18, 1.0, v19
	v_rcp_f32_e32 v20, v18
	v_add_f32_e32 v18, 1.0, v21
	v_rcp_f32_e32 v21, v18
.LBB0_646:
	v_cvt_f32_i32_e32 v17, v17
	v_cvt_f32_i32_e32 v16, v16
	s_nop 0
	v_cvt_pk_bf16_f32 v30, v24, v25
	s_nop 0
	v_cvt_pk_bf16_f32 v31, v22, v23
	s_nop 0
	v_cvt_pk_bf16_f32 v32, v28, v29
	v_cvt_f32_i32_e32 v15, v15
	v_cvt_f32_i32_e32 v14, v14
	s_nop 0
	v_cvt_pk_bf16_f32 v33, v20, v21
	v_cvt_f32_i32_e32 v21, v13
	v_cvt_f32_i32_e32 v11, v11
	v_cvt_f32_i32_e32 v10, v10
	v_cvt_f32_i32_e32 v20, v12
	v_mul_f32_e32 v18, v180, v181
	v_pk_mul_f32 v[16:17], v[18:19], v[16:17] op_sel_hi:[0,1]
	v_pk_mul_f32 v[14:15], v[18:19], v[14:15] op_sel_hi:[0,1]
	v_pk_mul_f32 v[12:13], v[80:81], v[16:17]
	v_pk_mul_f32 v[10:11], v[18:19], v[10:11] op_sel_hi:[0,1]
	v_pk_mul_f32 v[16:17], v[18:19], v[20:21] op_sel_hi:[0,1]
	v_pk_mul_f32 v[14:15], v[78:79], v[14:15]
	v_pk_mul_f32 v[16:17], v[76:77], v[16:17]
	s_and_b64 vcc, exec, s[6:7]
	v_pk_mul_f32 v[20:21], v[74:75], v[10:11]
	global_store_dwordx4 v[26:27], v[30:33], off offset:1024
	s_cbranch_vccnz .LBB0_648
	v_mul_f32_e32 v10, 0xbfb8aa3b, v14
	v_exp_f32_e32 v10, v10
	v_mul_f32_e32 v11, 0xbfb8aa3b, v15
	v_exp_f32_e32 v11, v11
	v_add_f32_e32 v10, 1.0, v10
	v_rcp_f32_e32 v14, v10
	v_mul_f32_e32 v10, 0xbfb8aa3b, v12
	v_add_f32_e32 v11, 1.0, v11
	v_exp_f32_e32 v10, v10
	v_mul_f32_e32 v12, 0xbfb8aa3b, v13
	v_exp_f32_e32 v13, v12
	v_rcp_f32_e32 v15, v11
	v_mul_f32_e32 v11, 0xbfb8aa3b, v20
	v_exp_f32_e32 v11, v11
	v_add_f32_e32 v10, 1.0, v10
	v_rcp_f32_e32 v12, v10
	v_add_f32_e32 v10, 1.0, v13
	v_mul_f32_e32 v13, 0xbfb8aa3b, v21
	v_exp_f32_e32 v19, v13
	v_rcp_f32_e32 v13, v10
	v_add_f32_e32 v10, 1.0, v11
	v_mul_f32_e32 v11, 0xbfb8aa3b, v16
	v_exp_f32_e32 v11, v11
	v_mul_f32_e32 v16, 0xbfb8aa3b, v17
	v_exp_f32_e32 v17, v16
	v_rcp_f32_e32 v20, v10
	v_add_f32_e32 v10, 1.0, v19
	v_rcp_f32_e32 v21, v10
	v_add_f32_e32 v10, 1.0, v11
	v_rcp_f32_e32 v16, v10
	v_add_f32_e32 v10, 1.0, v17
	v_rcp_f32_e32 v17, v10
.LBB0_648:
	v_add_u32_e32 v10, 0xb0, v162
	v_ashrrev_i32_e32 v11, 31, v10
	v_mul_lo_u32 v22, s2, v11
	v_mul_lo_u32 v23, s3, v10
	v_mad_u64_u32 v[10:11], s[2:3], s2, v10, 0
	v_cvt_f32_i32_e32 v7, v7
	v_cvt_f32_i32_e32 v9, v9
	v_cvt_f32_i32_e32 v8, v8
	v_cvt_f32_i32_e32 v6, v6
	v_add3_u32 v11, v11, v22, v23
	s_nop 0
	v_cvt_pk_bf16_f32 v22, v14, v15
	s_nop 0
	v_cvt_pk_bf16_f32 v23, v12, v13
	s_nop 0
	v_cvt_pk_bf16_f32 v24, v20, v21
	s_nop 0
	v_cvt_pk_bf16_f32 v25, v16, v17
	v_cvt_f32_i32_e32 v15, v3
	v_cvt_f32_i32_e32 v17, v5
	v_cvt_f32_i32_e32 v16, v4
	v_cvt_f32_i32_e32 v14, v2
	v_mov_b32_e32 v19, v18
	v_mov_b32_e32 v12, v18
	v_mov_b32_e32 v13, v18
	v_pk_mul_f32 v[8:9], v[12:13], v[8:9]
	v_pk_mul_f32 v[6:7], v[18:19], v[6:7]
	v_pk_mul_f32 v[2:3], v[64:65], v[8:9]
	v_pk_mul_f32 v[4:5], v[62:63], v[6:7]
	v_pk_mul_f32 v[6:7], v[12:13], v[16:17]
	v_pk_mul_f32 v[8:9], v[18:19], v[14:15]
	s_mov_b64 s[98:99], 0x3800
	v_lshl_add_u64 v[10:11], v[248:249], 0, s[98:99]
	v_pk_mul_f32 v[6:7], v[60:61], v[6:7]
	s_and_b64 vcc, exec, s[6:7]
	v_pk_mul_f32 v[8:9], v[58:59], v[8:9]
	global_store_dwordx4 v[10:11], v[22:25], off
	s_cbranch_vccnz .LBB0_650
	v_mul_f32_e32 v4, 0xbfb8aa3b, v4
	v_mul_f32_e32 v5, 0xbfb8aa3b, v5
	v_mul_f32_e32 v2, 0xbfb8aa3b, v2
	v_mul_f32_e32 v3, 0xbfb8aa3b, v3
	v_mul_f32_e32 v8, 0xbfb8aa3b, v8
	v_mul_f32_e32 v9, 0xbfb8aa3b, v9
	v_mul_f32_e32 v6, 0xbfb8aa3b, v6
	v_mul_f32_e32 v7, 0xbfb8aa3b, v7
	v_exp_f32_e32 v4, v4
	v_exp_f32_e32 v5, v5
	v_exp_f32_e32 v2, v2
	v_exp_f32_e32 v3, v3
	v_exp_f32_e32 v8, v8
	v_exp_f32_e32 v9, v9
	v_exp_f32_e32 v6, v6
	v_exp_f32_e32 v7, v7
	v_add_f32_e32 v4, 1.0, v4
	v_add_f32_e32 v5, 1.0, v5
	v_add_f32_e32 v2, 1.0, v2
	v_add_f32_e32 v3, 1.0, v3
	v_add_f32_e32 v8, 1.0, v8
	v_add_f32_e32 v9, 1.0, v9
	v_add_f32_e32 v6, 1.0, v6
	v_add_f32_e32 v7, 1.0, v7
	v_rcp_f32_e32 v4, v4
	v_rcp_f32_e32 v5, v5
	v_rcp_f32_e32 v2, v2
	v_rcp_f32_e32 v3, v3
	v_rcp_f32_e32 v8, v8
	v_rcp_f32_e32 v9, v9
	v_rcp_f32_e32 v6, v6
	v_rcp_f32_e32 v7, v7
.LBB0_650:
	s_andn2_b64 vcc, exec, s[4:5]
	s_mov_b64 s[2:3], -1
	s_nop 0
	v_cvt_pk_bf16_f32 v12, v4, v5
	s_nop 0
	v_cvt_pk_bf16_f32 v13, v2, v3
	s_nop 0
	v_cvt_pk_bf16_f32 v14, v8, v9
	s_nop 0
	v_cvt_pk_bf16_f32 v15, v6, v7
	global_store_dwordx4 v[10:11], v[12:15], off offset:1024
	s_cbranch_vccnz .LBB0_599
	s_andn2_b64 vcc, exec, s[16:17]
	s_cbranch_vccnz .LBB0_598
	s_barrier
	s_branch .LBB0_598

;     __device__ __forceinline__ void load_row(RowIn& R, int r, int col0) const {
; #pragma unroll
;         for (int bj = 0; bj < 2; ++bj) {
;             if (MODE == 2) R.g[bj] = *(const u32x4*)(GT + (size_t)r * 8192 + col0 + bj * HALF);
;             if (MODE == 3) { R.g[bj] = *(const u32x4*)(GT + (size_t)r * 8192 + 4096 + col0 + bj * HALF); R.a[bj] = *(const u32x4*)(AD + (size_t)r * 4096 + col0 + bj * HALF); } }
;     }
;     __device__ __forceinline__ void operator()(AccRef acc, const Unit& u, int wr, int wc, int fr, int fq) const {
;         const int row0 = u.pm * BM + wr * 64 + fr, col0 = u.pn * BM + wc * 32 + 8 * fq;
;         RowIn cur, nxt;
;         if (MODE >= 2) load_row(cur, row0, col0);
; #pragma unroll
;         for (int s = 0; s < 8; ++s) { const int ai = s >> 2, m = s & 3; const int r = row0 + ai * HALF + m * 16; bf16_t* rowp = O + (size_t)r * ldc + col0;
;                 if (MODE >= 2 && s + 1 < 8) load_row(nxt, row0 + ((s + 1) >> 2) * HALF + ((s + 1) & 3) * 16, col0);
;                 float rs = 1.f; if (MODE == 1) rs = __builtin_amdgcn_rsqf(rstd[r] * (1.0f / 4096.0f) + 1e-6f);
;                 float mx = 0.f;
; #pragma unroll
;                 for (int bj = 0; bj < 2; ++bj) { f32x4 v0 = acc[ai][bj][m][0], v1 = acc[ai][bj][m][1];
;                     if (MODE == 1) { v0 = v0 * rs; v1 = v1 * rs;
; #pragma unroll
;                         for (int j = 0; j < 4; ++j) { const float a = v0[j] > 0.f ? v0[j] : 0.f, b = v1[j] > 0.f ? v1[j] : 0.f; v0[j] = a * a; v1[j] = b * b; } }
;                     if (MODE == 2) { f32x4 g0, g1; unpack8(cur.g[bj], g0, g1); v0 = v0 * g0; v1 = v1 * g1; }
;                     if (MODE == 3) { f32x4 g0, g1, a0, a1; unpack8(cur.g[bj], g0, g1); unpack8(cur.a[bj], a0, a1);
;                         v0 = a0 + v0 * g0; v1 = a1 + v1 * g1;
; #pragma unroll
;                         for (int j = 0; j < 4; ++j) mx = fmaxf(mx, fmaxf(fabsf(v0[j]), fabsf(v1[j]))); }
;                     *(u32x4*)(rowp + bj * HALF) = pack8(v0, v1); }
;                 if (MODE == 3) { mx = fmaxf(mx, __shfl_xor(mx, 16)); mx = fmaxf(mx, __shfl_xor(mx, 32)); if (fq == 0) atomicMax(RM + r, __builtin_bit_cast(unsigned, mx)); }
;                 if (MODE >= 2) cur = nxt; }
.LBB0_1541:
	s_lshl_b32 s98, s20, 5
	s_add_i32 s98, s98, s44
	s_lshl_b32 s98, s98, 17
	v_and_b32_e32 v248, 63, v0
	v_lshlrev_b32_e32 v248, 4, v248
	v_lshrrev_b32_e32 v249, 6, v0
	v_lshl_add_u32 v248, v249, 14, v248
	v_add_u32_e32 v248, s98, v248
	v_mov_b32_e32 v249, 0
	v_lshl_add_u64 v[248:249], s[6:7], 0, v[248:249]
	s_lshl_b32 s98, s20, 4
	s_add_i32 s98, s98, s44
	s_lshl_b32 s98, s98, 17
	v_and_b32_e32 v250, 63, v0
	v_lshlrev_b32_e32 v250, 4, v250
	v_lshrrev_b32_e32 v251, 6, v0
	v_lshl_add_u32 v250, v251, 14, v250
	v_add_u32_e32 v250, s98, v250
	v_mov_b32_e32 v251, 0
	v_lshl_add_u64 v[250:251], s[2:3], 0, v[250:251]
	v_mov_b32_e32 v146, v0
	s_andn2_b64 vcc, exec, s[4:5]
	v_ashrrev_i32_e32 v147, 2, v146
	v_and_b32_e32 v147, 0xffffffc0, v147
	v_lshl_add_u32 v147, s20, 8, v147
	v_and_or_b32 v148, v146, 15, v147
	v_lshrrev_b32_e32 v146, 1, v146
	v_and_b32_e32 v146, 0x78, v146
	v_lshl_or_b32 v146, s44, 8, v146
	v_ashrrev_i32_e32 v149, 31, v148
	v_lshlrev_b64 v[150:151], 14, v[148:149]
	v_ashrrev_i32_e32 v147, 31, v146
	v_lshl_add_u64 v[150:151], s[6:7], 0, v[150:151]
	v_lshlrev_b64 v[146:147], 1, v[146:147]
	v_or_b32_e32 v174, 16, v148
	s_mov_b64 s[98:99], 0x0
	v_lshl_add_u64 v[150:151], v[248:249], 0, s[98:99]
	v_ashrrev_i32_e32 v175, 31, v174
	global_load_dwordx4 v[158:161], v[150:151], off
	global_load_dwordx4 v[162:165], v[150:151], off offset:1024
	v_lshlrev_b64 v[150:151], 14, v[174:175]
	v_lshl_add_u64 v[150:151], s[6:7], 0, v[150:151]
	s_mov_b64 s[98:99], 0x800
	v_lshl_add_u64 v[150:151], v[248:249], 0, s[98:99]
	global_load_dwordx4 v[166:169], v[150:151], off
	global_load_dwordx4 v[170:173], v[150:151], off offset:1024
	v_or_b32_e32 v150, 32, v148
	v_ashrrev_i32_e32 v151, 31, v150
	v_lshlrev_b64 v[176:177], 13, v[148:149]
	v_lshlrev_b64 v[178:179], 14, v[150:151]
	v_lshl_add_u64 v[176:177], s[2:3], 0, v[176:177]
	v_lshl_add_u64 v[178:179], s[6:7], 0, v[178:179]
	s_mov_b64 s[98:99], 0x0
	v_lshl_add_u64 v[176:177], v[250:251], 0, s[98:99]
	s_mov_b64 s[98:99], 0x1000
	v_lshl_add_u64 v[178:179], v[248:249], 0, s[98:99]
	v_or_b32_e32 v152, 48, v148
	v_ashrrev_i32_e32 v153, 31, v152
	v_lshlrev_b64 v[174:175], 13, v[174:175]
	v_lshlrev_b64 v[180:181], 14, v[152:153]
	v_lshl_add_u64 v[174:175], s[2:3], 0, v[174:175]
	v_lshl_add_u64 v[180:181], s[6:7], 0, v[180:181]
	s_mov_b64 s[98:99], 0x800
	v_lshl_add_u64 v[174:175], v[250:251], 0, s[98:99]
	s_mov_b64 s[98:99], 0x1800
	v_lshl_add_u64 v[180:181], v[248:249], 0, s[98:99]
	s_mov_b64 s[4:5], -1
	s_waitcnt vmcnt(0)
	v_lshlrev_b32_e32 v182, 16, v158
	v_and_b32_e32 v183, 0xffff0000, v158
	v_lshlrev_b32_e32 v158, 16, v159
	v_and_b32_e32 v159, 0xffff0000, v159
	v_lshlrev_b32_e32 v184, 16, v160
	v_and_b32_e32 v185, 0xffff0000, v160
	v_lshlrev_b32_e32 v160, 16, v161
	v_and_b32_e32 v161, 0xffff0000, v161
	v_lshlrev_b32_e32 v186, 16, v162
	v_and_b32_e32 v187, 0xffff0000, v162
	v_lshlrev_b32_e32 v162, 16, v163
	v_and_b32_e32 v163, 0xffff0000, v163
	v_lshlrev_b32_e32 v188, 16, v164
	v_and_b32_e32 v189, 0xffff0000, v164
	v_lshlrev_b32_e32 v164, 16, v165
	v_and_b32_e32 v165, 0xffff0000, v165
	v_pk_mul_f32 v[128:129], v[128:129], v[158:159]
	v_pk_mul_f32 v[126:127], v[126:127], v[182:183]
	v_pk_mul_f32 v[124:125], v[124:125], v[160:161]
	v_pk_mul_f32 v[122:123], v[122:123], v[184:185]
	v_pk_mul_f32 v[120:121], v[120:121], v[162:163]
	v_pk_mul_f32 v[118:119], v[118:119], v[186:187]
	v_pk_mul_f32 v[158:159], v[112:113], v[164:165]
	v_pk_mul_f32 v[160:161], v[110:111], v[188:189]
	s_nop 0
	v_cvt_pk_bf16_f32 v110, v126, v127
	s_nop 0
	v_cvt_pk_bf16_f32 v111, v128, v129
	s_nop 0
	v_cvt_pk_bf16_f32 v112, v122, v123
	s_nop 0
	v_cvt_pk_bf16_f32 v113, v124, v125
	global_store_dwordx4 v[176:177], v[110:113], off
	v_lshlrev_b32_e32 v162, 16, v166
	v_and_b32_e32 v163, 0xffff0000, v166
	s_nop 0
	v_cvt_pk_bf16_f32 v110, v118, v119
	s_nop 0
	v_cvt_pk_bf16_f32 v111, v120, v121
	s_nop 0
	v_cvt_pk_bf16_f32 v112, v160, v161
	s_nop 0
	v_cvt_pk_bf16_f32 v113, v158, v159
	global_load_dwordx4 v[118:121], v[178:179], off
	v_lshlrev_b32_e32 v164, 16, v167
	v_and_b32_e32 v165, 0xffff0000, v167
	v_lshlrev_b32_e32 v166, 16, v168
	v_and_b32_e32 v167, 0xffff0000, v168
	v_lshlrev_b32_e32 v124, 16, v171
	v_and_b32_e32 v125, 0xffff0000, v171
	global_store_dwordx4 v[176:177], v[110:113], off offset:1024
	v_pk_mul_f32 v[158:159], v[106:107], v[166:167]
	v_pk_mul_f32 v[124:125], v[104:105], v[124:125]
	global_load_dwordx4 v[104:107], v[178:179], off offset:1024
	v_lshlrev_b32_e32 v168, 16, v169
	v_and_b32_e32 v169, 0xffff0000, v169
	v_lshlrev_b32_e32 v126, 16, v172
	v_and_b32_e32 v127, 0xffff0000, v172
	v_lshlrev_b32_e32 v128, 16, v173
	v_and_b32_e32 v129, 0xffff0000, v173
	v_lshlrev_b32_e32 v122, 16, v170
	v_and_b32_e32 v123, 0xffff0000, v170
	v_pk_mul_f32 v[116:117], v[116:117], v[164:165]
	v_pk_mul_f32 v[114:115], v[114:115], v[162:163]
	v_pk_mul_f32 v[108:109], v[108:109], v[168:169]
	v_pk_mul_f32 v[110:111], v[100:101], v[128:129]
	v_pk_mul_f32 v[112:113], v[98:99], v[126:127]
	s_nop 0
	v_cvt_pk_bf16_f32 v98, v114, v115
	s_nop 0
	v_cvt_pk_bf16_f32 v99, v116, v117
	s_nop 0
	v_cvt_pk_bf16_f32 v100, v158, v159
	s_nop 0
	v_cvt_pk_bf16_f32 v101, v108, v109
	v_pk_mul_f32 v[102:103], v[102:103], v[122:123]
	global_store_dwordx4 v[174:175], v[98:101], off
	v_lshlrev_b64 v[116:117], 13, v[152:153]
	v_lshl_add_u64 v[116:117], s[2:3], 0, v[116:117]
	s_nop 0
	v_cvt_pk_bf16_f32 v98, v102, v103
	s_nop 0
	v_cvt_pk_bf16_f32 v99, v124, v125
	s_nop 0
	v_cvt_pk_bf16_f32 v100, v112, v113
	s_nop 0
	v_cvt_pk_bf16_f32 v101, v110, v111
	global_load_dwordx4 v[108:111], v[180:181], off
	v_lshlrev_b64 v[102:103], 13, v[150:151]
	global_store_dwordx4 v[174:175], v[98:101], off offset:1024
	global_load_dwordx4 v[112:115], v[180:181], off offset:1024
	v_lshl_add_u64 v[102:103], s[2:3], 0, v[102:103]
	v_add_u32_e32 v98, 0x80, v148
	v_ashrrev_i32_e32 v99, 31, v98
	v_lshlrev_b64 v[122:123], 14, v[98:99]
	v_lshl_add_u64 v[122:123], s[6:7], 0, v[122:123]
	s_mov_b64 s[98:99], 0x1000
	v_lshl_add_u64 v[102:103], v[250:251], 0, s[98:99]
	v_add_u32_e32 v100, 0x90, v148
	s_mov_b64 s[98:99], 0x2000
	v_lshl_add_u64 v[122:123], v[248:249], 0, s[98:99]
	v_ashrrev_i32_e32 v101, 31, v100
	v_lshlrev_b64 v[124:125], 14, v[100:101]
	v_lshl_add_u64 v[124:125], s[6:7], 0, v[124:125]
	s_mov_b64 s[98:99], 0x1800
	v_lshl_add_u64 v[116:117], v[250:251], 0, s[98:99]
	s_mov_b64 s[98:99], 0x2800
	v_lshl_add_u64 v[124:125], v[248:249], 0, s[98:99]
	s_waitcnt vmcnt(6)
;     __device__ __forceinline__ void load_row(RowIn& R, int r, int col0) const {
; #pragma unroll
;         for (int bj = 0; bj < 2; ++bj) {
;             if (MODE == 2) R.g[bj] = *(const u32x4*)(GT + (size_t)r * 8192 + col0 + bj * HALF);
;             if (MODE == 3) { R.g[bj] = *(const u32x4*)(GT + (size_t)r * 8192 + 4096 + col0 + bj * HALF); R.a[bj] = *(const u32x4*)(AD + (size_t)r * 4096 + col0 + bj * HALF); } }
;     }
;     __device__ __forceinline__ void operator()(AccRef acc, const Unit& u, int wr, int wc, int fr, int fq) const {
;         const int row0 = u.pm * BM + wr * 64 + fr, col0 = u.pn * BM + wc * 32 + 8 * fq;
;         RowIn cur, nxt;
;         if (MODE >= 2) load_row(cur, row0, col0);
; #pragma unroll
;         for (int s = 0; s < 8; ++s) { const int ai = s >> 2, m = s & 3; const int r = row0 + ai * HALF + m * 16; bf16_t* rowp = O + (size_t)r * ldc + col0;
;                 if (MODE >= 2 && s + 1 < 8) load_row(nxt, row0 + ((s + 1) >> 2) * HALF + ((s + 1) & 3) * 16, col0);
;                 float rs = 1.f; if (MODE == 1) rs = __builtin_amdgcn_rsqf(rstd[r] * (1.0f / 4096.0f) + 1e-6f);
;                 float mx = 0.f;
; #pragma unroll
;                 for (int bj = 0; bj < 2; ++bj) { f32x4 v0 = acc[ai][bj][m][0], v1 = acc[ai][bj][m][1];
;                     if (MODE == 1) { v0 = v0 * rs; v1 = v1 * rs;
; #pragma unroll
;                         for (int j = 0; j < 4; ++j) { const float a = v0[j] > 0.f ? v0[j] : 0.f, b = v1[j] > 0.f ? v1[j] : 0.f; v0[j] = a * a; v1[j] = b * b; } }
;                     if (MODE == 2) { f32x4 g0, g1; unpack8(cur.g[bj], g0, g1); v0 = v0 * g0; v1 = v1 * g1; }
;                     if (MODE == 3) { f32x4 g0, g1, a0, a1; unpack8(cur.g[bj], g0, g1); unpack8(cur.a[bj], a0, a1);
;                         v0 = a0 + v0 * g0; v1 = a1 + v1 * g1;
; #pragma unroll
;                         for (int j = 0; j < 4; ++j) mx = fmaxf(mx, fmaxf(fabsf(v0[j]), fabsf(v1[j]))); }
;                     *(u32x4*)(rowp + bj * HALF) = pack8(v0, v1); }
;                 if (MODE == 3) { mx = fmaxf(mx, __shfl_xor(mx, 16)); mx = fmaxf(mx, __shfl_xor(mx, 32)); if (fq == 0) atomicMax(RM + r, __builtin_bit_cast(unsigned, mx)); }
;                 if (MODE >= 2) cur = nxt; }
	v_lshlrev_b32_e32 v126, 16, v118
	v_and_b32_e32 v127, 0xffff0000, v118
	v_lshlrev_b32_e32 v118, 16, v119
	v_and_b32_e32 v119, 0xffff0000, v119
	v_lshlrev_b32_e32 v128, 16, v120
	v_and_b32_e32 v129, 0xffff0000, v120
	v_lshlrev_b32_e32 v120, 16, v121
	v_and_b32_e32 v121, 0xffff0000, v121
	v_pk_mul_f32 v[96:97], v[96:97], v[118:119]
	v_pk_mul_f32 v[94:95], v[94:95], v[126:127]
	v_pk_mul_f32 v[118:119], v[92:93], v[120:121]
	v_pk_mul_f32 v[92:93], v[90:91], v[128:129]
	s_nop 0
	v_cvt_pk_bf16_f32 v90, v94, v95
	s_nop 0
	v_cvt_pk_bf16_f32 v91, v96, v97
	s_waitcnt vmcnt(4)
	v_lshlrev_b32_e32 v94, 16, v104
	v_and_b32_e32 v95, 0xffff0000, v104
	v_lshlrev_b32_e32 v96, 16, v105
	v_and_b32_e32 v97, 0xffff0000, v105
	v_lshlrev_b32_e32 v104, 16, v106
	v_and_b32_e32 v105, 0xffff0000, v106
	v_lshlrev_b32_e32 v106, 16, v107
	v_and_b32_e32 v107, 0xffff0000, v107
	s_nop 0
	v_cvt_pk_bf16_f32 v92, v92, v93
	s_nop 0
	v_cvt_pk_bf16_f32 v93, v118, v119
	global_store_dwordx4 v[102:103], v[90:93], off
	v_pk_mul_f32 v[80:81], v[80:81], v[96:97]
	v_pk_mul_f32 v[78:79], v[78:79], v[94:95]
	v_pk_mul_f32 v[90:91], v[76:77], v[106:107]
	v_pk_mul_f32 v[76:77], v[74:75], v[104:105]
	s_nop 0
	v_cvt_pk_bf16_f32 v74, v78, v79
	s_nop 0
	v_cvt_pk_bf16_f32 v75, v80, v81
	s_waitcnt vmcnt(3)
	v_lshlrev_b32_e32 v92, 16, v108
	s_nop 0
	v_cvt_pk_bf16_f32 v76, v76, v77
	s_nop 0
	v_cvt_pk_bf16_f32 v77, v90, v91
	global_load_dwordx4 v[78:81], v[122:123], off
	v_and_b32_e32 v93, 0xffff0000, v108
	v_lshlrev_b32_e32 v94, 16, v109
	v_and_b32_e32 v95, 0xffff0000, v109
	v_lshlrev_b32_e32 v96, 16, v110
	v_and_b32_e32 v97, 0xffff0000, v110
	v_lshlrev_b32_e32 v104, 16, v111
	v_and_b32_e32 v105, 0xffff0000, v111
	global_store_dwordx4 v[102:103], v[74:77], off offset:1024
	v_pk_mul_f32 v[88:89], v[88:89], v[94:95]
	v_pk_mul_f32 v[86:87], v[86:87], v[92:93]
	v_pk_mul_f32 v[90:91], v[84:85], v[104:105]
	v_pk_mul_f32 v[84:85], v[82:83], v[96:97]
	s_waitcnt vmcnt(3)
	v_lshlrev_b32_e32 v92, 16, v112
	v_and_b32_e32 v93, 0xffff0000, v112
	v_lshlrev_b32_e32 v94, 16, v113
	v_and_b32_e32 v95, 0xffff0000, v113
	v_lshlrev_b32_e32 v96, 16, v114
	v_and_b32_e32 v97, 0xffff0000, v114
	v_lshlrev_b32_e32 v102, 16, v115
	v_and_b32_e32 v103, 0xffff0000, v115
	global_load_dwordx4 v[74:77], v[122:123], off offset:1024
	s_nop 0
	v_cvt_pk_bf16_f32 v82, v86, v87
	v_pk_mul_f32 v[72:73], v[72:73], v[94:95]
	v_pk_mul_f32 v[70:71], v[70:71], v[92:93]
	v_pk_mul_f32 v[86:87], v[68:69], v[102:103]
	v_pk_mul_f32 v[68:69], v[66:67], v[96:97]
	s_nop 0
	v_cvt_pk_bf16_f32 v83, v88, v89
	s_nop 0
	v_cvt_pk_bf16_f32 v84, v84, v85
	s_nop 0
	v_cvt_pk_bf16_f32 v85, v90, v91
	global_store_dwordx4 v[116:117], v[82:85], off
	s_nop 0
	v_cvt_pk_bf16_f32 v66, v70, v71
	s_nop 0
	v_cvt_pk_bf16_f32 v67, v72, v73
	s_nop 0
	v_cvt_pk_bf16_f32 v68, v68, v69
	s_nop 0
	v_cvt_pk_bf16_f32 v69, v86, v87
	global_load_dwordx4 v[70:73], v[124:125], off
	s_nop 0
	v_add_u32_e32 v82, 0xa0, v148
	global_store_dwordx4 v[116:117], v[66:69], off offset:1024
	global_load_dwordx4 v[66:69], v[124:125], off offset:1024
	v_ashrrev_i32_e32 v83, 31, v82
	v_lshlrev_b64 v[86:87], 13, v[98:99]
	v_lshlrev_b64 v[90:91], 14, v[82:83]
	v_lshl_add_u64 v[86:87], s[2:3], 0, v[86:87]
	v_add_u32_e32 v84, 0xb0, v148
	v_lshl_add_u64 v[90:91], s[6:7], 0, v[90:91]
	s_mov_b64 s[98:99], 0x2000
	v_lshl_add_u64 v[86:87], v[250:251], 0, s[98:99]
	v_ashrrev_i32_e32 v85, 31, v84
	s_mov_b64 s[98:99], 0x3000
	v_lshl_add_u64 v[90:91], v[248:249], 0, s[98:99]
	v_lshlrev_b64 v[88:89], 13, v[100:101]
	v_lshlrev_b64 v[92:93], 14, v[84:85]
	v_lshl_add_u64 v[88:89], s[2:3], 0, v[88:89]
	v_lshl_add_u64 v[92:93], s[6:7], 0, v[92:93]
	s_mov_b64 s[98:99], 0x2800
	v_lshl_add_u64 v[88:89], v[250:251], 0, s[98:99]
	s_mov_b64 s[98:99], 0x3800
	v_lshl_add_u64 v[92:93], v[248:249], 0, s[98:99]
	s_waitcnt vmcnt(6)
	v_lshlrev_b32_e32 v94, 16, v78
	v_and_b32_e32 v95, 0xffff0000, v78
	v_lshlrev_b32_e32 v78, 16, v79
	v_and_b32_e32 v79, 0xffff0000, v79
	v_lshlrev_b32_e32 v96, 16, v80
	v_and_b32_e32 v97, 0xffff0000, v80
	v_lshlrev_b32_e32 v80, 16, v81
	v_and_b32_e32 v81, 0xffff0000, v81
	v_pk_mul_f32 v[64:65], v[64:65], v[78:79]
	v_pk_mul_f32 v[62:63], v[62:63], v[94:95]
	v_pk_mul_f32 v[78:79], v[60:61], v[80:81]
	v_pk_mul_f32 v[60:61], v[58:59], v[96:97]
	s_nop 0
	v_cvt_pk_bf16_f32 v58, v62, v63
	s_nop 0
	v_cvt_pk_bf16_f32 v59, v64, v65
	s_waitcnt vmcnt(4)
	v_lshlrev_b32_e32 v62, 16, v74
	v_and_b32_e32 v63, 0xffff0000, v74
	v_lshlrev_b32_e32 v64, 16, v75
	v_and_b32_e32 v65, 0xffff0000, v75
	v_lshlrev_b32_e32 v74, 16, v76
	v_and_b32_e32 v75, 0xffff0000, v76
	v_lshlrev_b32_e32 v76, 16, v77
	v_and_b32_e32 v77, 0xffff0000, v77
	s_nop 0
	v_cvt_pk_bf16_f32 v60, v60, v61
	s_nop 0
	v_cvt_pk_bf16_f32 v61, v78, v79
	global_store_dwordx4 v[86:87], v[58:61], off
	v_pk_mul_f32 v[48:49], v[48:49], v[64:65]
	v_pk_mul_f32 v[46:47], v[46:47], v[62:63]
	v_pk_mul_f32 v[58:59], v[44:45], v[76:77]
	v_pk_mul_f32 v[44:45], v[42:43], v[74:75]
	s_waitcnt vmcnt(3)
;     __device__ __forceinline__ void load_row(RowIn& R, int r, int col0) const {
; #pragma unroll
;         for (int bj = 0; bj < 2; ++bj) {
;             if (MODE == 2) R.g[bj] = *(const u32x4*)(GT + (size_t)r * 8192 + col0 + bj * HALF);
;             if (MODE == 3) { R.g[bj] = *(const u32x4*)(GT + (size_t)r * 8192 + 4096 + col0 + bj * HALF); R.a[bj] = *(const u32x4*)(AD + (size_t)r * 4096 + col0 + bj * HALF); } }
;     }
;     __device__ __forceinline__ void operator()(AccRef acc, const Unit& u, int wr, int wc, int fr, int fq) const {
;         const int row0 = u.pm * BM + wr * 64 + fr, col0 = u.pn * BM + wc * 32 + 8 * fq;
;         RowIn cur, nxt;
;         if (MODE >= 2) load_row(cur, row0, col0);
; #pragma unroll
;         for (int s = 0; s < 8; ++s) { const int ai = s >> 2, m = s & 3; const int r = row0 + ai * HALF + m * 16; bf16_t* rowp = O + (size_t)r * ldc + col0;
;                 if (MODE >= 2 && s + 1 < 8) load_row(nxt, row0 + ((s + 1) >> 2) * HALF + ((s + 1) & 3) * 16, col0);
;                 float rs = 1.f; if (MODE == 1) rs = __builtin_amdgcn_rsqf(rstd[r] * (1.0f / 4096.0f) + 1e-6f);
;                 float mx = 0.f;
; #pragma unroll
;                 for (int bj = 0; bj < 2; ++bj) { f32x4 v0 = acc[ai][bj][m][0], v1 = acc[ai][bj][m][1];
;                     if (MODE == 1) { v0 = v0 * rs; v1 = v1 * rs;
; #pragma unroll
;                         for (int j = 0; j < 4; ++j) { const float a = v0[j] > 0.f ? v0[j] : 0.f, b = v1[j] > 0.f ? v1[j] : 0.f; v0[j] = a * a; v1[j] = b * b; } }
;                     if (MODE == 2) { f32x4 g0, g1; unpack8(cur.g[bj], g0, g1); v0 = v0 * g0; v1 = v1 * g1; }
;                     if (MODE == 3) { f32x4 g0, g1, a0, a1; unpack8(cur.g[bj], g0, g1); unpack8(cur.a[bj], a0, a1);
;                         v0 = a0 + v0 * g0; v1 = a1 + v1 * g1;
; #pragma unroll
;                         for (int j = 0; j < 4; ++j) mx = fmaxf(mx, fmaxf(fabsf(v0[j]), fabsf(v1[j]))); }
;                     *(u32x4*)(rowp + bj * HALF) = pack8(v0, v1); }
;                 if (MODE == 3) { mx = fmaxf(mx, __shfl_xor(mx, 16)); mx = fmaxf(mx, __shfl_xor(mx, 32)); if (fq == 0) atomicMax(RM + r, __builtin_bit_cast(unsigned, mx)); }
;                 if (MODE >= 2) cur = nxt; }
	v_lshlrev_b32_e32 v60, 16, v70
	v_and_b32_e32 v61, 0xffff0000, v70
	v_lshlrev_b32_e32 v62, 16, v71
	v_and_b32_e32 v63, 0xffff0000, v71
	v_lshlrev_b32_e32 v64, 16, v72
	v_and_b32_e32 v65, 0xffff0000, v72
	v_lshlrev_b32_e32 v70, 16, v73
	s_nop 0
	v_cvt_pk_bf16_f32 v42, v46, v47
	s_nop 0
	v_cvt_pk_bf16_f32 v43, v48, v49
	s_nop 0
	v_cvt_pk_bf16_f32 v44, v44, v45
	s_nop 0
	v_cvt_pk_bf16_f32 v45, v58, v59
	global_load_dwordx4 v[46:49], v[90:91], off
	v_and_b32_e32 v71, 0xffff0000, v73
	v_pk_mul_f32 v[56:57], v[56:57], v[62:63]
	v_pk_mul_f32 v[54:55], v[54:55], v[60:61]
	v_pk_mul_f32 v[58:59], v[52:53], v[70:71]
	v_pk_mul_f32 v[52:53], v[50:51], v[64:65]
	global_store_dwordx4 v[86:87], v[42:45], off offset:1024
	s_waitcnt vmcnt(3)
	v_lshlrev_b32_e32 v60, 16, v66
	v_and_b32_e32 v61, 0xffff0000, v66
	v_lshlrev_b32_e32 v62, 16, v67
	v_and_b32_e32 v63, 0xffff0000, v67
	v_lshlrev_b32_e32 v64, 16, v68
	v_and_b32_e32 v65, 0xffff0000, v68
	v_lshlrev_b32_e32 v66, 16, v69
	v_and_b32_e32 v67, 0xffff0000, v69
	global_load_dwordx4 v[42:45], v[90:91], off offset:1024
	s_nop 0
	v_cvt_pk_bf16_f32 v50, v54, v55
	v_pk_mul_f32 v[40:41], v[40:41], v[62:63]
	v_pk_mul_f32 v[38:39], v[38:39], v[60:61]
	v_pk_mul_f32 v[54:55], v[36:37], v[66:67]
	v_pk_mul_f32 v[36:37], v[34:35], v[64:65]
	s_nop 0
	v_cvt_pk_bf16_f32 v51, v56, v57
	s_nop 0
	v_cvt_pk_bf16_f32 v52, v52, v53
	s_nop 0
	v_cvt_pk_bf16_f32 v53, v58, v59
	global_store_dwordx4 v[88:89], v[50:53], off
	s_nop 0
	v_cvt_pk_bf16_f32 v34, v38, v39
	s_nop 0
	v_cvt_pk_bf16_f32 v35, v40, v41
	s_nop 0
	v_cvt_pk_bf16_f32 v36, v36, v37
	s_nop 0
	v_cvt_pk_bf16_f32 v37, v54, v55
	global_load_dwordx4 v[38:41], v[92:93], off
	s_nop 0
	v_lshlrev_b64 v[50:51], 13, v[82:83]
	global_store_dwordx4 v[88:89], v[34:37], off offset:1024
	global_load_dwordx4 v[34:37], v[92:93], off offset:1024
	v_lshl_add_u64 v[50:51], s[2:3], 0, v[50:51]
	s_mov_b64 s[98:99], 0x3000
	v_lshl_add_u64 v[50:51], v[250:251], 0, s[98:99]
	v_lshlrev_b64 v[52:53], 13, v[84:85]
	v_lshl_add_u64 v[52:53], s[2:3], 0, v[52:53]
	s_mov_b64 s[98:99], 0x3800
	v_lshl_add_u64 v[52:53], v[250:251], 0, s[98:99]
	s_waitcnt vmcnt(6)
	v_lshlrev_b32_e32 v54, 16, v46
	v_and_b32_e32 v55, 0xffff0000, v46
	v_lshlrev_b32_e32 v46, 16, v47
	v_and_b32_e32 v47, 0xffff0000, v47
	v_lshlrev_b32_e32 v56, 16, v48
	v_and_b32_e32 v57, 0xffff0000, v48
	v_lshlrev_b32_e32 v48, 16, v49
	v_and_b32_e32 v49, 0xffff0000, v49
	v_pk_mul_f32 v[32:33], v[32:33], v[46:47]
	v_pk_mul_f32 v[30:31], v[30:31], v[54:55]
	v_pk_mul_f32 v[46:47], v[28:29], v[48:49]
	v_pk_mul_f32 v[28:29], v[26:27], v[56:57]
	s_nop 0
	v_cvt_pk_bf16_f32 v26, v30, v31
	s_nop 0
	v_cvt_pk_bf16_f32 v27, v32, v33
	s_waitcnt vmcnt(4)
	v_lshlrev_b32_e32 v30, 16, v42
	s_nop 0
	v_cvt_pk_bf16_f32 v28, v28, v29
	s_nop 0
	v_cvt_pk_bf16_f32 v29, v46, v47
	v_and_b32_e32 v31, 0xffff0000, v42
	v_lshlrev_b32_e32 v32, 16, v43
	v_and_b32_e32 v33, 0xffff0000, v43
	v_lshlrev_b32_e32 v42, 16, v44
	v_and_b32_e32 v43, 0xffff0000, v44
	v_lshlrev_b32_e32 v44, 16, v45
	v_and_b32_e32 v45, 0xffff0000, v45
	global_store_dwordx4 v[50:51], v[26:29], off
	v_pk_mul_f32 v[20:21], v[20:21], v[32:33]
	v_pk_mul_f32 v[18:19], v[18:19], v[30:31]
	v_pk_mul_f32 v[26:27], v[16:17], v[44:45]
	s_waitcnt vmcnt(3)
	v_lshlrev_b32_e32 v28, 16, v38
	v_and_b32_e32 v29, 0xffff0000, v38
	v_lshlrev_b32_e32 v30, 16, v39
	v_and_b32_e32 v31, 0xffff0000, v39
	v_lshlrev_b32_e32 v32, 16, v40
	v_and_b32_e32 v33, 0xffff0000, v40
	v_lshlrev_b32_e32 v38, 16, v41
	v_and_b32_e32 v39, 0xffff0000, v41
	v_pk_mul_f32 v[16:17], v[14:15], v[42:43]
	s_nop 0
	v_cvt_pk_bf16_f32 v14, v18, v19
	s_nop 0
	v_cvt_pk_bf16_f32 v15, v20, v21
	v_pk_mul_f32 v[20:21], v[22:23], v[28:29]
	v_pk_mul_f32 v[22:23], v[12:13], v[38:39]
	v_pk_mul_f32 v[12:13], v[10:11], v[32:33]
	s_nop 0
	v_cvt_pk_bf16_f32 v16, v16, v17
	s_nop 0
	v_cvt_pk_bf16_f32 v17, v26, v27
	v_pk_mul_f32 v[18:19], v[24:25], v[30:31]
	global_store_dwordx4 v[50:51], v[14:17], off offset:1024
	s_nop 0
	v_cvt_pk_bf16_f32 v10, v20, v21
	s_nop 0
	v_cvt_pk_bf16_f32 v11, v18, v19
	s_nop 0
	v_cvt_pk_bf16_f32 v12, v12, v13
	s_nop 0
	v_cvt_pk_bf16_f32 v13, v22, v23
	global_store_dwordx4 v[52:53], v[10:13], off
	s_waitcnt vmcnt(3)
	v_lshlrev_b32_e32 v14, 16, v34
	v_and_b32_e32 v15, 0xffff0000, v34
	v_lshlrev_b32_e32 v10, 16, v36
	v_and_b32_e32 v11, 0xffff0000, v36
	v_lshlrev_b32_e32 v12, 16, v37
	v_and_b32_e32 v13, 0xffff0000, v37
	v_lshlrev_b32_e32 v16, 16, v35
	v_and_b32_e32 v17, 0xffff0000, v35
	v_pk_mul_f32 v[12:13], v[4:5], v[12:13]
	v_pk_mul_f32 v[4:5], v[2:3], v[10:11]
	v_pk_mul_f32 v[8:9], v[8:9], v[16:17]
	v_pk_mul_f32 v[6:7], v[6:7], v[14:15]
	s_nop 0
	s_nop 0
	v_cvt_pk_bf16_f32 v2, v6, v7
	s_nop 0
	v_cvt_pk_bf16_f32 v3, v8, v9
	s_nop 0
	v_cvt_pk_bf16_f32 v4, v4, v5
	s_nop 0
	v_cvt_pk_bf16_f32 v5, v12, v13
	global_store_dwordx4 v[52:53], v[2:5], off offset:1024
	s_cbranch_vccnz .LBB0_1530
	s_andn2_b64 vcc, exec, s[0:1]
	s_cbranch_vccnz .LBB0_1529
	s_barrier
	s_branch .LBB0_1529

;     __device__ __forceinline__ void load_row(RowIn& R, int r, int col0) const {
; #pragma unroll
;         for (int bj = 0; bj < 2; ++bj) {
;             if (MODE == 2) R.g[bj] = *(const u32x4*)(GT + (size_t)r * 8192 + col0 + bj * HALF);
;             if (MODE == 3) { R.g[bj] = *(const u32x4*)(GT + (size_t)r * 8192 + 4096 + col0 + bj * HALF); R.a[bj] = *(const u32x4*)(AD + (size_t)r * 4096 + col0 + bj * HALF); } }
;     }
;     __device__ __forceinline__ void operator()(AccRef acc, const Unit& u, int wr, int wc, int fr, int fq) const {
;         const int row0 = u.pm * BM + wr * 64 + fr, col0 = u.pn * BM + wc * 32 + 8 * fq;
;         RowIn cur, nxt;
;         if (MODE >= 2) load_row(cur, row0, col0);
; #pragma unroll
;         for (int s = 0; s < 8; ++s) { const int ai = s >> 2, m = s & 3; const int r = row0 + ai * HALF + m * 16; bf16_t* rowp = O + (size_t)r * ldc + col0;
;                 if (MODE >= 2 && s + 1 < 8) load_row(nxt, row0 + ((s + 1) >> 2) * HALF + ((s + 1) & 3) * 16, col0);
;                 float rs = 1.f; if (MODE == 1) rs = __builtin_amdgcn_rsqf(rstd[r] * (1.0f / 4096.0f) + 1e-6f);
;                 float mx = 0.f;
; #pragma unroll
;                 for (int bj = 0; bj < 2; ++bj) { f32x4 v0 = acc[ai][bj][m][0], v1 = acc[ai][bj][m][1];
;                     if (MODE == 1) { v0 = v0 * rs; v1 = v1 * rs;
; #pragma unroll
;                         for (int j = 0; j < 4; ++j) { const float a = v0[j] > 0.f ? v0[j] : 0.f, b = v1[j] > 0.f ? v1[j] : 0.f; v0[j] = a * a; v1[j] = b * b; } }
;                     if (MODE == 2) { f32x4 g0, g1; unpack8(cur.g[bj], g0, g1); v0 = v0 * g0; v1 = v1 * g1; }
;                     if (MODE == 3) { f32x4 g0, g1, a0, a1; unpack8(cur.g[bj], g0, g1); unpack8(cur.a[bj], a0, a1);
;                         v0 = a0 + v0 * g0; v1 = a1 + v1 * g1;
; #pragma unroll
;                         for (int j = 0; j < 4; ++j) mx = fmaxf(mx, fmaxf(fabsf(v0[j]), fabsf(v1[j]))); }
;                     *(u32x4*)(rowp + bj * HALF) = pack8(v0, v1); }
;                 if (MODE == 3) { mx = fmaxf(mx, __shfl_xor(mx, 16)); mx = fmaxf(mx, __shfl_xor(mx, 32)); if (fq == 0) atomicMax(RM + r, __builtin_bit_cast(unsigned, mx)); }
;                 if (MODE >= 2) cur = nxt; }
.LBB0_1568:
	s_lshl_b32 s98, s26, 5
	s_add_i32 s98, s98, s6
	s_add_i32 s98, s98, 16
	s_lshl_b32 s98, s98, 17
	v_and_b32_e32 v248, 63, v0
	v_lshlrev_b32_e32 v248, 4, v248
	v_lshrrev_b32_e32 v249, 6, v0
	v_lshl_add_u32 v248, v249, 14, v248
	v_add_u32_e32 v248, s98, v248
	v_mov_b32_e32 v249, 0
	v_lshl_add_u64 v[248:249], s[8:9], 0, v[248:249]
	s_lshl_b32 s98, s26, 4
	s_add_i32 s98, s98, s6
	s_lshl_b32 s98, s98, 17
	v_and_b32_e32 v250, 63, v0
	v_lshlrev_b32_e32 v250, 4, v250
	v_lshrrev_b32_e32 v251, 6, v0
	v_lshl_add_u32 v250, v251, 14, v250
	v_add_u32_e32 v250, s98, v250
	v_mov_b32_e32 v251, 0
	v_lshl_add_u64 v[250:251], s[10:11], 0, v[250:251]
	v_mov_b32_e32 v130, v0
	s_nop 0
	v_ashrrev_i32_e32 v131, 2, v130
	v_and_b32_e32 v131, 0xffffffc0, v131
	v_lshl_add_u32 v131, s26, 8, v131
	v_bfe_u32 v174, v130, 4, 2
	v_and_or_b32 v166, v130, 15, v131
	v_lshrrev_b32_e32 v130, 1, v130
	v_and_b32_e32 v130, 0x60, v130
	v_lshl_or_b32 v130, s6, 8, v130
	v_lshl_or_b32 v162, v174, 3, v130
	v_ashrrev_i32_e32 v167, 31, v166
	v_ashrrev_i32_e32 v163, 31, v162
	v_lshlrev_b64 v[170:171], 13, v[166:167]
	v_lshlrev_b64 v[164:165], 1, v[162:163]
	v_lshl_add_u64 v[130:131], s[10:11], 0, v[170:171]
	v_lshl_add_u64 v[130:131], v[130:131], 0, v[164:165]
	s_mov_b64 s[98:99], 0x0
	v_lshl_add_u64 v[252:253], v[250:251], 0, s[98:99]
	global_load_dwordx4 v[180:183], v[252:253], off
	global_load_dwordx4 v[184:187], v[252:253], off offset:1024
	v_lshlrev_b64 v[130:131], 14, v[166:167]
	v_lshl_add_u64 v[130:131], s[8:9], 0, v[130:131]
	v_lshl_add_u64 v[130:131], v[130:131], 0, v[164:165]
	v_add_co_u32_e32 v130, vcc, s44, v130
	v_or_b32_e32 v168, 16, v166
	s_nop 0
	v_addc_co_u32_e32 v131, vcc, 0, v131, vcc
	s_mov_b64 s[98:99], 0x0
	v_lshl_add_u64 v[246:247], v[248:249], 0, s[98:99]
	global_load_dwordx4 v[188:191], v[246:247], off
	global_load_dwordx4 v[192:195], v[246:247], off offset:1024
	v_ashrrev_i32_e32 v169, 31, v168
	v_lshlrev_b64 v[130:131], 14, v[168:169]
	v_lshl_add_u64 v[130:131], s[8:9], 0, v[130:131]
	v_lshlrev_b64 v[172:173], 13, v[168:169]
	v_lshl_add_u64 v[130:131], v[130:131], 0, v[164:165]
	v_lshl_add_u64 v[132:133], s[10:11], 0, v[172:173]
	v_add_co_u32_e32 v134, vcc, s44, v130
	v_lshl_add_u64 v[132:133], v[132:133], 0, v[164:165]
	s_nop 0
	v_addc_co_u32_e32 v135, vcc, 0, v131, vcc
	s_mov_b64 s[98:99], 0x800
	v_lshl_add_u64 v[252:253], v[250:251], 0, s[98:99]
	global_load_dwordx4 v[138:141], v[252:253], off
	s_nop 0
	global_load_dwordx4 v[130:133], v[252:253], off offset:1024
	s_nop 0
	s_mov_b64 s[98:99], 0x800
	v_lshl_add_u64 v[246:247], v[248:249], 0, s[98:99]
	global_load_dwordx4 v[142:145], v[246:247], off
	s_nop 0
	global_load_dwordx4 v[134:137], v[246:247], off offset:1024
	v_cmp_eq_u32_e64 s[6:7], 0, v174
	v_lshl_add_u64 v[170:171], s[2:3], 0, v[170:171]
	v_lshl_add_u64 v[170:171], v[170:171], 0, v[164:165]
	s_waitcnt vmcnt(0)
	v_lshlrev_b32_e32 v174, 16, v180
	v_and_b32_e32 v175, 0xffff0000, v180
	v_lshlrev_b32_e32 v196, 16, v182
	v_and_b32_e32 v197, 0xffff0000, v182
	v_lshlrev_b32_e32 v180, 16, v181
	v_and_b32_e32 v181, 0xffff0000, v181
	v_lshlrev_b32_e32 v182, 16, v183
	v_and_b32_e32 v183, 0xffff0000, v183
	v_lshlrev_b32_e32 v200, 16, v186
	v_lshlrev_b32_e32 v202, 16, v188
	v_and_b32_e32 v203, 0xffff0000, v188
	v_lshlrev_b32_e32 v204, 16, v190
	v_and_b32_e32 v205, 0xffff0000, v190
	v_and_b32_e32 v201, 0xffff0000, v186
	v_lshlrev_b32_e32 v186, 16, v187
	v_and_b32_e32 v187, 0xffff0000, v187
	v_lshlrev_b32_e32 v188, 16, v189
	v_and_b32_e32 v189, 0xffff0000, v189
	v_lshlrev_b32_e32 v190, 16, v191
	v_and_b32_e32 v191, 0xffff0000, v191
	v_lshlrev_b32_e32 v208, 16, v194
	v_and_b32_e32 v209, 0xffff0000, v194
	v_lshlrev_b32_e32 v194, 16, v195
	v_and_b32_e32 v195, 0xffff0000, v195
	v_pk_fma_f32 v[126:127], v[126:127], v[202:203], v[174:175]
	v_pk_fma_f32 v[122:123], v[122:123], v[204:205], v[196:197]
	v_lshlrev_b32_e32 v198, 16, v184
	v_and_b32_e32 v199, 0xffff0000, v184
	v_lshlrev_b32_e32 v206, 16, v192
	v_and_b32_e32 v207, 0xffff0000, v192
	v_pk_fma_f32 v[128:129], v[128:129], v[188:189], v[180:181]
	v_pk_fma_f32 v[124:125], v[124:125], v[190:191], v[182:183]
	v_pk_fma_f32 v[174:175], v[116:117], v[194:195], v[186:187]
	v_max_f32_e64 v116, |v126|, |v122|
	v_max_f32_e64 v117, |v127|, |v123|
	v_lshlrev_b32_e32 v184, 16, v185
	v_and_b32_e32 v185, 0xffff0000, v185
	v_lshlrev_b32_e32 v192, 16, v193
	v_and_b32_e32 v193, 0xffff0000, v193
	v_pk_fma_f32 v[118:119], v[118:119], v[206:207], v[198:199]
	v_pk_fma_f32 v[182:183], v[114:115], v[208:209], v[200:201]
	v_max_f32_e64 v180, |v128|, |v124|
	v_max_f32_e64 v181, |v129|, |v125|
	v_max3_f32 v116, v116, 0, v117
	v_pk_fma_f32 v[120:121], v[120:121], v[192:193], v[184:185]
	s_nop 0
	v_cvt_pk_bf16_f32 v114, v126, v127
	v_max_f32_e64 v126, |v118|, |v182|
	v_max3_f32 v116, v116, v180, v181
	v_max_f32_e64 v117, |v119|, |v183|
	v_max3_f32 v116, v116, v126, v117
	v_max_f32_e64 v117, |v120|, |v174|
	v_max_f32_e64 v126, |v121|, |v175|
	v_max3_f32 v126, v116, v117, v126
	v_and_b32_e32 v117, 64, v179
	v_xor_b32_e32 v116, 16, v179
	v_add_u32_e32 v127, 64, v117
	v_cmp_lt_i32_e32 vcc, v116, v127
	s_nop 0
	v_cvt_pk_bf16_f32 v115, v128, v129
	s_nop 1
	v_cndmask_b32_e32 v116, v179, v116, vcc
	v_lshlrev_b32_e32 v180, 2, v116
	ds_bpermute_b32 v128, v180, v126
	s_nop 0
	v_cvt_pk_bf16_f32 v116, v122, v123
	s_nop 0
	v_cvt_pk_bf16_f32 v117, v124, v125
	global_store_dwordx4 v[170:171], v[114:117], off
	s_nop 1
	v_xor_b32_e32 v115, 32, v179
	v_cmp_lt_i32_e32 vcc, v115, v127
	s_waitcnt lgkmcnt(0)
	v_max_f32_e32 v114, v128, v128
	v_max_f32_e32 v114, v126, v114
	v_cndmask_b32_e32 v115, v179, v115, vcc
	v_lshlrev_b32_e32 v181, 2, v115
	ds_bpermute_b32 v115, v181, v114
	s_nop 0
	v_cvt_pk_bf16_f32 v116, v118, v119
	s_nop 0
	v_cvt_pk_bf16_f32 v117, v120, v121
	s_nop 0
	v_cvt_pk_bf16_f32 v118, v182, v183
	s_nop 0
	v_cvt_pk_bf16_f32 v119, v174, v175
	global_store_dwordx4 v[170:171], v[116:119], off offset:256
	s_and_saveexec_b64 s[26:27], s[6:7]
	s_cbranch_execz .LBB0_1570
	s_waitcnt lgkmcnt(0)
	v_max_f32_e32 v115, v115, v115
	v_max_f32_e32 v114, v114, v114
	v_lshl_add_u64 v[116:117], v[166:167], 2, s[12:13]
	v_max_f32_e32 v114, v114, v115
	global_atomic_umax v[116:117], v114, off
;     __device__ __forceinline__ void load_row(RowIn& R, int r, int col0) const {
; #pragma unroll
;         for (int bj = 0; bj < 2; ++bj) {
;             if (MODE == 2) R.g[bj] = *(const u32x4*)(GT + (size_t)r * 8192 + col0 + bj * HALF);
;             if (MODE == 3) { R.g[bj] = *(const u32x4*)(GT + (size_t)r * 8192 + 4096 + col0 + bj * HALF); R.a[bj] = *(const u32x4*)(AD + (size_t)r * 4096 + col0 + bj * HALF); } }
;     }
;     __device__ __forceinline__ void operator()(AccRef acc, const Unit& u, int wr, int wc, int fr, int fq) const {
;         const int row0 = u.pm * BM + wr * 64 + fr, col0 = u.pn * BM + wc * 32 + 8 * fq;
;         RowIn cur, nxt;
;         if (MODE >= 2) load_row(cur, row0, col0);
; #pragma unroll
;         for (int s = 0; s < 8; ++s) { const int ai = s >> 2, m = s & 3; const int r = row0 + ai * HALF + m * 16; bf16_t* rowp = O + (size_t)r * ldc + col0;
;                 if (MODE >= 2 && s + 1 < 8) load_row(nxt, row0 + ((s + 1) >> 2) * HALF + ((s + 1) & 3) * 16, col0);
;                 float rs = 1.f; if (MODE == 1) rs = __builtin_amdgcn_rsqf(rstd[r] * (1.0f / 4096.0f) + 1e-6f);
;                 float mx = 0.f;
; #pragma unroll
;                 for (int bj = 0; bj < 2; ++bj) { f32x4 v0 = acc[ai][bj][m][0], v1 = acc[ai][bj][m][1];
;                     if (MODE == 1) { v0 = v0 * rs; v1 = v1 * rs;
; #pragma unroll
;                         for (int j = 0; j < 4; ++j) { const float a = v0[j] > 0.f ? v0[j] : 0.f, b = v1[j] > 0.f ? v1[j] : 0.f; v0[j] = a * a; v1[j] = b * b; } }
;                     if (MODE == 2) { f32x4 g0, g1; unpack8(cur.g[bj], g0, g1); v0 = v0 * g0; v1 = v1 * g1; }
;                     if (MODE == 3) { f32x4 g0, g1, a0, a1; unpack8(cur.g[bj], g0, g1); unpack8(cur.a[bj], a0, a1);
;                         v0 = a0 + v0 * g0; v1 = a1 + v1 * g1;
; #pragma unroll
;                         for (int j = 0; j < 4; ++j) mx = fmaxf(mx, fmaxf(fabsf(v0[j]), fabsf(v1[j]))); }
;                     *(u32x4*)(rowp + bj * HALF) = pack8(v0, v1); }
;                 if (MODE == 3) { mx = fmaxf(mx, __shfl_xor(mx, 16)); mx = fmaxf(mx, __shfl_xor(mx, 32)); if (fq == 0) atomicMax(RM + r, __builtin_bit_cast(unsigned, mx)); }
;                 if (MODE >= 2) cur = nxt; }
.LBB0_1570:
	s_or_b64 exec, exec, s[26:27]
	v_or_b32_e32 v170, 32, v166
	v_ashrrev_i32_e32 v171, 31, v170
	s_waitcnt lgkmcnt(0)
	v_lshlrev_b64 v[114:115], 14, v[170:171]
	v_lshl_add_u64 v[114:115], s[8:9], 0, v[114:115]
	v_lshlrev_b64 v[174:175], 13, v[170:171]
	v_lshl_add_u64 v[114:115], v[114:115], 0, v[164:165]
	v_add_co_u32_e32 v114, vcc, 0x2000, v114
	v_lshl_add_u64 v[116:117], s[10:11], 0, v[174:175]
	s_nop 0
	v_addc_co_u32_e32 v115, vcc, 0, v115, vcc
	v_lshl_add_u64 v[116:117], v[116:117], 0, v[164:165]
	s_mov_b64 s[98:99], 0x1000
	v_lshl_add_u64 v[246:247], v[248:249], 0, s[98:99]
	global_load_dwordx4 v[126:129], v[246:247], off
	global_load_dwordx4 v[118:121], v[246:247], off offset:1024
	s_mov_b64 s[98:99], 0x1000
	v_lshl_add_u64 v[252:253], v[250:251], 0, s[98:99]
	global_load_dwordx4 v[122:125], v[252:253], off
	s_nop 0
	global_load_dwordx4 v[114:117], v[252:253], off offset:1024
	v_lshlrev_b32_e32 v182, 16, v142
	v_and_b32_e32 v183, 0xffff0000, v142
	v_lshlrev_b32_e32 v142, 16, v143
	v_and_b32_e32 v143, 0xffff0000, v143
	v_lshlrev_b32_e32 v184, 16, v144
	v_and_b32_e32 v185, 0xffff0000, v144
	v_lshlrev_b32_e32 v144, 16, v145
	v_and_b32_e32 v145, 0xffff0000, v145
	v_lshlrev_b32_e32 v186, 16, v138
	v_and_b32_e32 v187, 0xffff0000, v138
	v_lshlrev_b32_e32 v138, 16, v139
	v_and_b32_e32 v139, 0xffff0000, v139
	v_lshlrev_b32_e32 v188, 16, v140
	v_and_b32_e32 v189, 0xffff0000, v140
	v_lshlrev_b32_e32 v140, 16, v141
	v_and_b32_e32 v141, 0xffff0000, v141
	v_pk_fma_f32 v[112:113], v[112:113], v[142:143], v[138:139]
	v_pk_fma_f32 v[110:111], v[110:111], v[182:183], v[186:187]
	v_pk_fma_f32 v[138:139], v[108:109], v[144:145], v[140:141]
	v_pk_fma_f32 v[108:109], v[106:107], v[184:185], v[188:189]
	v_max_f32_e64 v140, |v113|, |v139|
	v_max_f32_e64 v106, |v110|, |v108|
	v_max_f32_e64 v107, |v111|, |v109|
	v_max3_f32 v106, v106, 0, v107
	v_max_f32_e64 v107, |v112|, |v138|
	v_max3_f32 v144, v106, v107, v140
	s_nop 0
	v_cvt_pk_bf16_f32 v106, v110, v111
	s_nop 0
	v_cvt_pk_bf16_f32 v107, v112, v113
	v_lshlrev_b32_e32 v110, 16, v134
	v_and_b32_e32 v111, 0xffff0000, v134
	v_lshlrev_b32_e32 v112, 16, v135
	v_and_b32_e32 v113, 0xffff0000, v135
	v_lshlrev_b32_e32 v134, 16, v136
	v_and_b32_e32 v135, 0xffff0000, v136
	v_lshlrev_b32_e32 v140, 16, v130
	v_and_b32_e32 v141, 0xffff0000, v130
	v_lshlrev_b32_e32 v130, 16, v131
	v_and_b32_e32 v131, 0xffff0000, v131
	v_lshlrev_b32_e32 v142, 16, v132
	v_and_b32_e32 v143, 0xffff0000, v132
	v_lshlrev_b32_e32 v136, 16, v137
	v_and_b32_e32 v137, 0xffff0000, v137
	v_lshlrev_b32_e32 v132, 16, v133
	v_and_b32_e32 v133, 0xffff0000, v133
	v_pk_fma_f32 v[104:105], v[104:105], v[112:113], v[130:131]
	v_pk_fma_f32 v[102:103], v[102:103], v[110:111], v[140:141]
	v_pk_fma_f32 v[112:113], v[98:99], v[134:135], v[142:143]
	v_pk_fma_f32 v[110:111], v[100:101], v[136:137], v[132:133]
	v_max_f32_e64 v98, |v102|, |v112|
	v_max_f32_e64 v99, |v103|, |v113|
	v_max3_f32 v98, v144, v98, v99
	v_max_f32_e64 v99, |v104|, |v110|
	v_max_f32_e64 v100, |v105|, |v111|
	v_max3_f32 v98, v98, v99, v100
	ds_bpermute_b32 v99, v180, v98
	v_lshl_add_u64 v[172:173], s[2:3], 0, v[172:173]
	v_lshl_add_u64 v[172:173], v[172:173], 0, v[164:165]
	s_nop 0
	v_cvt_pk_bf16_f32 v108, v108, v109
	s_nop 0
	v_cvt_pk_bf16_f32 v109, v138, v139
	s_waitcnt lgkmcnt(0)
	v_max_f32_e32 v99, v99, v99
	v_max_f32_e32 v98, v98, v99
	ds_bpermute_b32 v99, v181, v98
	global_store_dwordx4 v[172:173], v[106:109], off
	s_nop 0
	v_cvt_pk_bf16_f32 v100, v102, v103
	s_nop 0
	v_cvt_pk_bf16_f32 v101, v104, v105
	s_nop 0
	v_cvt_pk_bf16_f32 v102, v112, v113
	s_nop 0
	v_cvt_pk_bf16_f32 v103, v110, v111
	global_store_dwordx4 v[172:173], v[100:103], off offset:256
	s_and_saveexec_b64 s[26:27], s[6:7]
	s_cbranch_execz .LBB0_1572
	s_waitcnt lgkmcnt(0)
	v_max_f32_e32 v99, v99, v99
	v_max_f32_e32 v98, v98, v98
	v_lshl_add_u64 v[100:101], v[168:169], 2, s[12:13]
	v_max_f32_e32 v98, v98, v99
	global_atomic_umax v[100:101], v98, off
.LBB0_1572:
	s_or_b64 exec, exec, s[26:27]
	v_or_b32_e32 v130, 48, v166
	v_ashrrev_i32_e32 v131, 31, v130
	s_waitcnt lgkmcnt(0)
	v_lshlrev_b64 v[98:99], 14, v[130:131]
	v_lshl_add_u64 v[98:99], s[8:9], 0, v[98:99]
	v_lshlrev_b64 v[132:133], 13, v[130:131]
	v_lshl_add_u64 v[98:99], v[98:99], 0, v[164:165]
	v_add_co_u32_e32 v98, vcc, 0x2000, v98
	v_lshl_add_u64 v[100:101], s[10:11], 0, v[132:133]
	s_nop 0
	v_addc_co_u32_e32 v99, vcc, 0, v99, vcc
	v_lshl_add_u64 v[100:101], v[100:101], 0, v[164:165]
	s_mov_b64 s[98:99], 0x1800
	v_lshl_add_u64 v[246:247], v[248:249], 0, s[98:99]
	global_load_dwordx4 v[110:113], v[246:247], off
	global_load_dwordx4 v[102:105], v[246:247], off offset:1024
	s_mov_b64 s[98:99], 0x1800
	v_lshl_add_u64 v[252:253], v[250:251], 0, s[98:99]
	global_load_dwordx4 v[106:109], v[252:253], off
	s_nop 0
	global_load_dwordx4 v[98:101], v[252:253], off offset:1024
	s_waitcnt vmcnt(9)
	v_lshlrev_b32_e32 v136, 16, v126
	v_and_b32_e32 v137, 0xffff0000, v126
	v_lshlrev_b32_e32 v126, 16, v127
	v_and_b32_e32 v127, 0xffff0000, v127
	v_lshlrev_b32_e32 v138, 16, v128
	v_and_b32_e32 v139, 0xffff0000, v128
	v_lshlrev_b32_e32 v128, 16, v129
	v_and_b32_e32 v129, 0xffff0000, v129
	s_waitcnt vmcnt(7)
;     __device__ __forceinline__ void load_row(RowIn& R, int r, int col0) const {
; #pragma unroll
;         for (int bj = 0; bj < 2; ++bj) {
;             if (MODE == 2) R.g[bj] = *(const u32x4*)(GT + (size_t)r * 8192 + col0 + bj * HALF);
;             if (MODE == 3) { R.g[bj] = *(const u32x4*)(GT + (size_t)r * 8192 + 4096 + col0 + bj * HALF); R.a[bj] = *(const u32x4*)(AD + (size_t)r * 4096 + col0 + bj * HALF); } }
;     }
;     __device__ __forceinline__ void operator()(AccRef acc, const Unit& u, int wr, int wc, int fr, int fq) const {
;         const int row0 = u.pm * BM + wr * 64 + fr, col0 = u.pn * BM + wc * 32 + 8 * fq;
;         RowIn cur, nxt;
;         if (MODE >= 2) load_row(cur, row0, col0);
; #pragma unroll
;         for (int s = 0; s < 8; ++s) { const int ai = s >> 2, m = s & 3; const int r = row0 + ai * HALF + m * 16; bf16_t* rowp = O + (size_t)r * ldc + col0;
;                 if (MODE >= 2 && s + 1 < 8) load_row(nxt, row0 + ((s + 1) >> 2) * HALF + ((s + 1) & 3) * 16, col0);
;                 float rs = 1.f; if (MODE == 1) rs = __builtin_amdgcn_rsqf(rstd[r] * (1.0f / 4096.0f) + 1e-6f);
;                 float mx = 0.f;
; #pragma unroll
;                 for (int bj = 0; bj < 2; ++bj) { f32x4 v0 = acc[ai][bj][m][0], v1 = acc[ai][bj][m][1];
;                     if (MODE == 1) { v0 = v0 * rs; v1 = v1 * rs;
; #pragma unroll
;                         for (int j = 0; j < 4; ++j) { const float a = v0[j] > 0.f ? v0[j] : 0.f, b = v1[j] > 0.f ? v1[j] : 0.f; v0[j] = a * a; v1[j] = b * b; } }
;                     if (MODE == 2) { f32x4 g0, g1; unpack8(cur.g[bj], g0, g1); v0 = v0 * g0; v1 = v1 * g1; }
;                     if (MODE == 3) { f32x4 g0, g1, a0, a1; unpack8(cur.g[bj], g0, g1); unpack8(cur.a[bj], a0, a1);
;                         v0 = a0 + v0 * g0; v1 = a1 + v1 * g1;
; #pragma unroll
;                         for (int j = 0; j < 4; ++j) mx = fmaxf(mx, fmaxf(fabsf(v0[j]), fabsf(v1[j]))); }
;                     *(u32x4*)(rowp + bj * HALF) = pack8(v0, v1); }
;                 if (MODE == 3) { mx = fmaxf(mx, __shfl_xor(mx, 16)); mx = fmaxf(mx, __shfl_xor(mx, 32)); if (fq == 0) atomicMax(RM + r, __builtin_bit_cast(unsigned, mx)); }
;                 if (MODE >= 2) cur = nxt; }
	v_lshlrev_b32_e32 v140, 16, v122
	v_and_b32_e32 v141, 0xffff0000, v122
	v_lshlrev_b32_e32 v122, 16, v123
	v_and_b32_e32 v123, 0xffff0000, v123
	v_lshlrev_b32_e32 v142, 16, v124
	v_and_b32_e32 v143, 0xffff0000, v124
	v_lshlrev_b32_e32 v124, 16, v125
	v_and_b32_e32 v125, 0xffff0000, v125
	v_pk_fma_f32 v[96:97], v[96:97], v[126:127], v[122:123]
	v_pk_fma_f32 v[94:95], v[94:95], v[136:137], v[140:141]
	v_pk_fma_f32 v[122:123], v[92:93], v[128:129], v[124:125]
	v_pk_fma_f32 v[92:93], v[90:91], v[138:139], v[142:143]
	v_max_f32_e64 v124, |v97|, |v123|
	v_max_f32_e64 v90, |v94|, |v92|
	v_max_f32_e64 v91, |v95|, |v93|
	v_max3_f32 v90, v90, 0, v91
	v_max_f32_e64 v91, |v96|, |v122|
	v_max3_f32 v128, v90, v91, v124
	s_nop 0
	v_cvt_pk_bf16_f32 v90, v94, v95
	s_nop 0
	v_cvt_pk_bf16_f32 v91, v96, v97
	v_lshlrev_b32_e32 v94, 16, v118
	v_and_b32_e32 v95, 0xffff0000, v118
	v_lshlrev_b32_e32 v96, 16, v119
	v_and_b32_e32 v97, 0xffff0000, v119
	v_lshlrev_b32_e32 v118, 16, v120
	v_and_b32_e32 v119, 0xffff0000, v120
	s_waitcnt vmcnt(6)
	v_lshlrev_b32_e32 v124, 16, v114
	v_and_b32_e32 v125, 0xffff0000, v114
	v_lshlrev_b32_e32 v114, 16, v115
	v_and_b32_e32 v115, 0xffff0000, v115
	v_lshlrev_b32_e32 v126, 16, v116
	v_and_b32_e32 v127, 0xffff0000, v116
	v_lshlrev_b32_e32 v120, 16, v121
	v_and_b32_e32 v121, 0xffff0000, v121
	v_lshlrev_b32_e32 v116, 16, v117
	v_and_b32_e32 v117, 0xffff0000, v117
	v_pk_fma_f32 v[88:89], v[88:89], v[96:97], v[114:115]
	v_pk_fma_f32 v[86:87], v[86:87], v[94:95], v[124:125]
	v_pk_fma_f32 v[96:97], v[82:83], v[118:119], v[126:127]
	v_pk_fma_f32 v[94:95], v[84:85], v[120:121], v[116:117]
	v_max_f32_e64 v82, |v86|, |v96|
	v_max_f32_e64 v83, |v87|, |v97|
	v_max3_f32 v82, v128, v82, v83
	v_max_f32_e64 v83, |v88|, |v94|
	v_max_f32_e64 v84, |v89|, |v95|
	v_max3_f32 v82, v82, v83, v84
	ds_bpermute_b32 v83, v180, v82
	v_lshl_add_u64 v[134:135], s[2:3], 0, v[174:175]
	v_lshl_add_u64 v[134:135], v[134:135], 0, v[164:165]
	s_nop 0
	v_cvt_pk_bf16_f32 v92, v92, v93
	s_nop 0
	v_cvt_pk_bf16_f32 v93, v122, v123
	s_waitcnt lgkmcnt(0)
	v_max_f32_e32 v83, v83, v83
	v_max_f32_e32 v82, v82, v83
	ds_bpermute_b32 v83, v181, v82
	global_store_dwordx4 v[134:135], v[90:93], off
	s_nop 0
	v_cvt_pk_bf16_f32 v84, v86, v87
	s_nop 0
	v_cvt_pk_bf16_f32 v85, v88, v89
	s_nop 0
	v_cvt_pk_bf16_f32 v86, v96, v97
	s_nop 0
	v_cvt_pk_bf16_f32 v87, v94, v95
	global_store_dwordx4 v[134:135], v[84:87], off offset:256
	s_and_saveexec_b64 s[26:27], s[6:7]
	s_cbranch_execz .LBB0_1574
	s_waitcnt lgkmcnt(0)
	v_max_f32_e32 v83, v83, v83
	v_max_f32_e32 v82, v82, v82
	v_lshl_add_u64 v[84:85], v[170:171], 2, s[12:13]
	v_max_f32_e32 v82, v82, v83
	global_atomic_umax v[84:85], v82, off
.LBB0_1574:
	s_or_b64 exec, exec, s[26:27]
	v_add_u32_e32 v114, 0x80, v166
	v_ashrrev_i32_e32 v115, 31, v114
	s_waitcnt lgkmcnt(0)
	v_lshlrev_b64 v[82:83], 14, v[114:115]
	v_lshl_add_u64 v[82:83], s[8:9], 0, v[82:83]
	v_lshlrev_b64 v[116:117], 13, v[114:115]
	v_lshl_add_u64 v[82:83], v[82:83], 0, v[164:165]
	v_add_co_u32_e32 v82, vcc, 0x2000, v82
	v_lshl_add_u64 v[84:85], s[10:11], 0, v[116:117]
	s_nop 0
	v_addc_co_u32_e32 v83, vcc, 0, v83, vcc
	v_lshl_add_u64 v[84:85], v[84:85], 0, v[164:165]
	s_mov_b64 s[98:99], 0x2000
	v_lshl_add_u64 v[246:247], v[248:249], 0, s[98:99]
	global_load_dwordx4 v[94:97], v[246:247], off
	global_load_dwordx4 v[86:89], v[246:247], off offset:1024
	s_mov_b64 s[98:99], 0x2000
	v_lshl_add_u64 v[252:253], v[250:251], 0, s[98:99]
	global_load_dwordx4 v[90:93], v[252:253], off
	s_nop 0
	global_load_dwordx4 v[82:85], v[252:253], off offset:1024
	s_waitcnt vmcnt(9)
	v_lshlrev_b32_e32 v120, 16, v110
	v_and_b32_e32 v121, 0xffff0000, v110
	v_lshlrev_b32_e32 v110, 16, v111
	v_and_b32_e32 v111, 0xffff0000, v111
	v_lshlrev_b32_e32 v122, 16, v112
	v_and_b32_e32 v123, 0xffff0000, v112
	v_lshlrev_b32_e32 v112, 16, v113
	v_and_b32_e32 v113, 0xffff0000, v113
	s_waitcnt vmcnt(7)
	v_lshlrev_b32_e32 v124, 16, v106
	v_and_b32_e32 v125, 0xffff0000, v106
	v_lshlrev_b32_e32 v106, 16, v107
	v_and_b32_e32 v107, 0xffff0000, v107
	v_lshlrev_b32_e32 v126, 16, v108
	v_and_b32_e32 v127, 0xffff0000, v108
	v_lshlrev_b32_e32 v108, 16, v109
	v_and_b32_e32 v109, 0xffff0000, v109
	v_pk_fma_f32 v[80:81], v[80:81], v[110:111], v[106:107]
	v_pk_fma_f32 v[78:79], v[78:79], v[120:121], v[124:125]
	v_pk_fma_f32 v[106:107], v[76:77], v[112:113], v[108:109]
	v_pk_fma_f32 v[76:77], v[74:75], v[122:123], v[126:127]
	v_max_f32_e64 v108, |v81|, |v107|
	v_max_f32_e64 v74, |v78|, |v76|
	v_max_f32_e64 v75, |v79|, |v77|
	v_max3_f32 v74, v74, 0, v75
	v_max_f32_e64 v75, |v80|, |v106|
	v_max3_f32 v112, v74, v75, v108
	s_nop 0
	v_cvt_pk_bf16_f32 v74, v78, v79
	s_nop 0
	v_cvt_pk_bf16_f32 v75, v80, v81
	v_lshlrev_b32_e32 v78, 16, v102
	v_and_b32_e32 v79, 0xffff0000, v102
	v_lshlrev_b32_e32 v80, 16, v103
	v_and_b32_e32 v81, 0xffff0000, v103
	v_lshlrev_b32_e32 v102, 16, v104
	v_and_b32_e32 v103, 0xffff0000, v104
	s_waitcnt vmcnt(6)
	v_lshlrev_b32_e32 v108, 16, v98
	v_and_b32_e32 v109, 0xffff0000, v98
	v_lshlrev_b32_e32 v98, 16, v99
	v_and_b32_e32 v99, 0xffff0000, v99
	v_lshlrev_b32_e32 v110, 16, v100
	v_and_b32_e32 v111, 0xffff0000, v100
	v_lshlrev_b32_e32 v104, 16, v105
	v_and_b32_e32 v105, 0xffff0000, v105
	v_lshlrev_b32_e32 v100, 16, v101
	v_and_b32_e32 v101, 0xffff0000, v101
	v_pk_fma_f32 v[72:73], v[72:73], v[80:81], v[98:99]
	v_pk_fma_f32 v[70:71], v[70:71], v[78:79], v[108:109]
	v_pk_fma_f32 v[80:81], v[66:67], v[102:103], v[110:111]
	v_pk_fma_f32 v[78:79], v[68:69], v[104:105], v[100:101]
	v_max_f32_e64 v66, |v70|, |v80|
	v_max_f32_e64 v67, |v71|, |v81|
	v_max3_f32 v66, v112, v66, v67
	v_max_f32_e64 v67, |v72|, |v78|
	v_max_f32_e64 v68, |v73|, |v79|
	v_max3_f32 v66, v66, v67, v68
	ds_bpermute_b32 v67, v180, v66
	v_lshl_add_u64 v[118:119], s[2:3], 0, v[132:133]
	v_lshl_add_u64 v[118:119], v[118:119], 0, v[164:165]
	s_nop 0
	v_cvt_pk_bf16_f32 v76, v76, v77
	s_nop 0
	v_cvt_pk_bf16_f32 v77, v106, v107
	s_waitcnt lgkmcnt(0)
	v_max_f32_e32 v67, v67, v67
	v_max_f32_e32 v66, v66, v67
	ds_bpermute_b32 v67, v181, v66
	global_store_dwordx4 v[118:119], v[74:77], off
	s_nop 0
	v_cvt_pk_bf16_f32 v68, v70, v71
	s_nop 0
	v_cvt_pk_bf16_f32 v69, v72, v73
	s_nop 0
	v_cvt_pk_bf16_f32 v70, v80, v81
	s_nop 0
	v_cvt_pk_bf16_f32 v71, v78, v79
	global_store_dwordx4 v[118:119], v[68:71], off offset:256
	s_and_saveexec_b64 s[26:27], s[6:7]
	s_cbranch_execz .LBB0_1576
	s_waitcnt lgkmcnt(0)
	v_max_f32_e32 v67, v67, v67
	v_max_f32_e32 v66, v66, v66
	v_lshl_add_u64 v[68:69], v[130:131], 2, s[12:13]
	v_max_f32_e32 v66, v66, v67
	global_atomic_umax v[68:69], v66, off
;     __device__ __forceinline__ void load_row(RowIn& R, int r, int col0) const {
; #pragma unroll
;         for (int bj = 0; bj < 2; ++bj) {
;             if (MODE == 2) R.g[bj] = *(const u32x4*)(GT + (size_t)r * 8192 + col0 + bj * HALF);
;             if (MODE == 3) { R.g[bj] = *(const u32x4*)(GT + (size_t)r * 8192 + 4096 + col0 + bj * HALF); R.a[bj] = *(const u32x4*)(AD + (size_t)r * 4096 + col0 + bj * HALF); } }
;     }
;     __device__ __forceinline__ void operator()(AccRef acc, const Unit& u, int wr, int wc, int fr, int fq) const {
;         const int row0 = u.pm * BM + wr * 64 + fr, col0 = u.pn * BM + wc * 32 + 8 * fq;
;         RowIn cur, nxt;
;         if (MODE >= 2) load_row(cur, row0, col0);
; #pragma unroll
;         for (int s = 0; s < 8; ++s) { const int ai = s >> 2, m = s & 3; const int r = row0 + ai * HALF + m * 16; bf16_t* rowp = O + (size_t)r * ldc + col0;
;                 if (MODE >= 2 && s + 1 < 8) load_row(nxt, row0 + ((s + 1) >> 2) * HALF + ((s + 1) & 3) * 16, col0);
;                 float rs = 1.f; if (MODE == 1) rs = __builtin_amdgcn_rsqf(rstd[r] * (1.0f / 4096.0f) + 1e-6f);
;                 float mx = 0.f;
; #pragma unroll
;                 for (int bj = 0; bj < 2; ++bj) { f32x4 v0 = acc[ai][bj][m][0], v1 = acc[ai][bj][m][1];
;                     if (MODE == 1) { v0 = v0 * rs; v1 = v1 * rs;
; #pragma unroll
;                         for (int j = 0; j < 4; ++j) { const float a = v0[j] > 0.f ? v0[j] : 0.f, b = v1[j] > 0.f ? v1[j] : 0.f; v0[j] = a * a; v1[j] = b * b; } }
;                     if (MODE == 2) { f32x4 g0, g1; unpack8(cur.g[bj], g0, g1); v0 = v0 * g0; v1 = v1 * g1; }
;                     if (MODE == 3) { f32x4 g0, g1, a0, a1; unpack8(cur.g[bj], g0, g1); unpack8(cur.a[bj], a0, a1);
;                         v0 = a0 + v0 * g0; v1 = a1 + v1 * g1;
; #pragma unroll
;                         for (int j = 0; j < 4; ++j) mx = fmaxf(mx, fmaxf(fabsf(v0[j]), fabsf(v1[j]))); }
;                     *(u32x4*)(rowp + bj * HALF) = pack8(v0, v1); }
;                 if (MODE == 3) { mx = fmaxf(mx, __shfl_xor(mx, 16)); mx = fmaxf(mx, __shfl_xor(mx, 32)); if (fq == 0) atomicMax(RM + r, __builtin_bit_cast(unsigned, mx)); }
;                 if (MODE >= 2) cur = nxt; }
.LBB0_1576:
	s_or_b64 exec, exec, s[26:27]
	v_or_b32_e32 v98, 16, v114
	v_ashrrev_i32_e32 v99, 31, v98
	s_waitcnt lgkmcnt(0)
	v_lshlrev_b64 v[66:67], 14, v[98:99]
	v_lshl_add_u64 v[66:67], s[8:9], 0, v[66:67]
	v_lshlrev_b64 v[100:101], 13, v[98:99]
	v_lshl_add_u64 v[66:67], v[66:67], 0, v[164:165]
	v_add_co_u32_e32 v66, vcc, 0x2000, v66
	v_lshl_add_u64 v[68:69], s[10:11], 0, v[100:101]
	s_nop 0
	v_addc_co_u32_e32 v67, vcc, 0, v67, vcc
	v_lshl_add_u64 v[68:69], v[68:69], 0, v[164:165]
	s_mov_b64 s[98:99], 0x2800
	v_lshl_add_u64 v[246:247], v[248:249], 0, s[98:99]
	global_load_dwordx4 v[78:81], v[246:247], off
	global_load_dwordx4 v[70:73], v[246:247], off offset:1024
	s_mov_b64 s[98:99], 0x2800
	v_lshl_add_u64 v[252:253], v[250:251], 0, s[98:99]
	global_load_dwordx4 v[74:77], v[252:253], off
	s_nop 0
	global_load_dwordx4 v[66:69], v[252:253], off offset:1024
	s_waitcnt vmcnt(9)
	v_lshlrev_b32_e32 v104, 16, v94
	v_and_b32_e32 v105, 0xffff0000, v94
	v_lshlrev_b32_e32 v94, 16, v95
	v_and_b32_e32 v95, 0xffff0000, v95
	v_lshlrev_b32_e32 v106, 16, v96
	v_and_b32_e32 v107, 0xffff0000, v96
	v_lshlrev_b32_e32 v96, 16, v97
	v_and_b32_e32 v97, 0xffff0000, v97
	s_waitcnt vmcnt(7)
	v_lshlrev_b32_e32 v108, 16, v90
	v_and_b32_e32 v109, 0xffff0000, v90
	v_lshlrev_b32_e32 v90, 16, v91
	v_and_b32_e32 v91, 0xffff0000, v91
	v_lshlrev_b32_e32 v110, 16, v92
	v_and_b32_e32 v111, 0xffff0000, v92
	v_lshlrev_b32_e32 v92, 16, v93
	v_and_b32_e32 v93, 0xffff0000, v93
	v_pk_fma_f32 v[64:65], v[64:65], v[94:95], v[90:91]
	v_pk_fma_f32 v[62:63], v[62:63], v[104:105], v[108:109]
	v_pk_fma_f32 v[90:91], v[60:61], v[96:97], v[92:93]
	v_pk_fma_f32 v[60:61], v[58:59], v[106:107], v[110:111]
	v_max_f32_e64 v92, |v65|, |v91|
	v_max_f32_e64 v58, |v62|, |v60|
	v_max_f32_e64 v59, |v63|, |v61|
	v_max3_f32 v58, v58, 0, v59
	v_max_f32_e64 v59, |v64|, |v90|
	v_max3_f32 v96, v58, v59, v92
	s_nop 0
	v_cvt_pk_bf16_f32 v58, v62, v63
	s_nop 0
	v_cvt_pk_bf16_f32 v59, v64, v65
	v_lshlrev_b32_e32 v62, 16, v86
	v_and_b32_e32 v63, 0xffff0000, v86
	v_lshlrev_b32_e32 v64, 16, v87
	v_and_b32_e32 v65, 0xffff0000, v87
	v_lshlrev_b32_e32 v86, 16, v88
	v_and_b32_e32 v87, 0xffff0000, v88
	s_waitcnt vmcnt(6)
	v_lshlrev_b32_e32 v92, 16, v82
	v_and_b32_e32 v93, 0xffff0000, v82
	v_lshlrev_b32_e32 v82, 16, v83
	v_and_b32_e32 v83, 0xffff0000, v83
	v_lshlrev_b32_e32 v94, 16, v84
	v_and_b32_e32 v95, 0xffff0000, v84
	v_lshlrev_b32_e32 v88, 16, v89
	v_and_b32_e32 v89, 0xffff0000, v89
	v_lshlrev_b32_e32 v84, 16, v85
	v_and_b32_e32 v85, 0xffff0000, v85
	v_pk_fma_f32 v[56:57], v[56:57], v[64:65], v[82:83]
	v_pk_fma_f32 v[54:55], v[54:55], v[62:63], v[92:93]
	v_pk_fma_f32 v[64:65], v[50:51], v[86:87], v[94:95]
	v_pk_fma_f32 v[62:63], v[52:53], v[88:89], v[84:85]
	v_max_f32_e64 v50, |v54|, |v64|
	v_max_f32_e64 v51, |v55|, |v65|
	v_max3_f32 v50, v96, v50, v51
	v_max_f32_e64 v51, |v56|, |v62|
	v_max_f32_e64 v52, |v57|, |v63|
	v_max3_f32 v50, v50, v51, v52
	ds_bpermute_b32 v51, v180, v50
	v_lshl_add_u64 v[102:103], s[2:3], 0, v[116:117]
	v_lshl_add_u64 v[102:103], v[102:103], 0, v[164:165]
	s_nop 0
	v_cvt_pk_bf16_f32 v60, v60, v61
	s_nop 0
	v_cvt_pk_bf16_f32 v61, v90, v91
	s_waitcnt lgkmcnt(0)
	v_max_f32_e32 v51, v51, v51
	v_max_f32_e32 v50, v50, v51
	ds_bpermute_b32 v51, v181, v50
	global_store_dwordx4 v[102:103], v[58:61], off
	s_nop 0
	v_cvt_pk_bf16_f32 v52, v54, v55
	s_nop 0
	v_cvt_pk_bf16_f32 v53, v56, v57
	s_nop 0
	v_cvt_pk_bf16_f32 v54, v64, v65
	s_nop 0
	v_cvt_pk_bf16_f32 v55, v62, v63
	global_store_dwordx4 v[102:103], v[52:55], off offset:256
	s_and_saveexec_b64 s[26:27], s[6:7]
	s_cbranch_execz .LBB0_1578
	s_waitcnt lgkmcnt(0)
	v_max_f32_e32 v51, v51, v51
	v_max_f32_e32 v50, v50, v50
	v_lshl_add_u64 v[52:53], v[114:115], 2, s[12:13]
	v_max_f32_e32 v50, v50, v51
	global_atomic_umax v[52:53], v50, off
.LBB0_1578:
	s_or_b64 exec, exec, s[26:27]
	v_or_b32_e32 v82, 32, v114
	v_ashrrev_i32_e32 v83, 31, v82
	s_waitcnt lgkmcnt(0)
	v_lshlrev_b64 v[50:51], 14, v[82:83]
	v_lshl_add_u64 v[50:51], s[8:9], 0, v[50:51]
	v_lshlrev_b64 v[84:85], 13, v[82:83]
	v_lshl_add_u64 v[50:51], v[50:51], 0, v[164:165]
	v_add_co_u32_e32 v50, vcc, 0x2000, v50
	v_lshl_add_u64 v[52:53], s[10:11], 0, v[84:85]
	s_nop 0
	v_addc_co_u32_e32 v51, vcc, 0, v51, vcc
	v_lshl_add_u64 v[52:53], v[52:53], 0, v[164:165]
	s_mov_b64 s[98:99], 0x3000
	v_lshl_add_u64 v[246:247], v[248:249], 0, s[98:99]
	global_load_dwordx4 v[62:65], v[246:247], off
	global_load_dwordx4 v[54:57], v[246:247], off offset:1024
	s_mov_b64 s[98:99], 0x3000
	v_lshl_add_u64 v[252:253], v[250:251], 0, s[98:99]
	global_load_dwordx4 v[58:61], v[252:253], off
	s_nop 0
	global_load_dwordx4 v[50:53], v[252:253], off offset:1024
	s_waitcnt vmcnt(9)
	v_lshlrev_b32_e32 v88, 16, v78
	v_and_b32_e32 v89, 0xffff0000, v78
	v_lshlrev_b32_e32 v78, 16, v79
	v_and_b32_e32 v79, 0xffff0000, v79
	v_lshlrev_b32_e32 v90, 16, v80
	v_and_b32_e32 v91, 0xffff0000, v80
	v_lshlrev_b32_e32 v80, 16, v81
	v_and_b32_e32 v81, 0xffff0000, v81
	s_waitcnt vmcnt(7)
	v_lshlrev_b32_e32 v92, 16, v74
	v_and_b32_e32 v93, 0xffff0000, v74
	v_lshlrev_b32_e32 v74, 16, v75
	v_and_b32_e32 v75, 0xffff0000, v75
	v_lshlrev_b32_e32 v94, 16, v76
	v_and_b32_e32 v95, 0xffff0000, v76
	v_lshlrev_b32_e32 v76, 16, v77
	v_and_b32_e32 v77, 0xffff0000, v77
	v_pk_fma_f32 v[48:49], v[48:49], v[78:79], v[74:75]
	v_pk_fma_f32 v[46:47], v[46:47], v[88:89], v[92:93]
	v_pk_fma_f32 v[74:75], v[44:45], v[80:81], v[76:77]
	v_pk_fma_f32 v[44:45], v[42:43], v[90:91], v[94:95]
	v_max_f32_e64 v76, |v49|, |v75|
	v_max_f32_e64 v42, |v46|, |v44|
	v_max_f32_e64 v43, |v47|, |v45|
	v_max3_f32 v42, v42, 0, v43
	v_max_f32_e64 v43, |v48|, |v74|
	v_max3_f32 v80, v42, v43, v76
	s_nop 0
	v_cvt_pk_bf16_f32 v42, v46, v47
	s_nop 0
	v_cvt_pk_bf16_f32 v43, v48, v49
	v_lshlrev_b32_e32 v46, 16, v70
	v_and_b32_e32 v47, 0xffff0000, v70
	v_lshlrev_b32_e32 v48, 16, v71
	v_and_b32_e32 v49, 0xffff0000, v71
	v_lshlrev_b32_e32 v70, 16, v72
	v_and_b32_e32 v71, 0xffff0000, v72
	s_waitcnt vmcnt(6)
;     __device__ __forceinline__ void load_row(RowIn& R, int r, int col0) const {
; #pragma unroll
;         for (int bj = 0; bj < 2; ++bj) {
;             if (MODE == 2) R.g[bj] = *(const u32x4*)(GT + (size_t)r * 8192 + col0 + bj * HALF);
;             if (MODE == 3) { R.g[bj] = *(const u32x4*)(GT + (size_t)r * 8192 + 4096 + col0 + bj * HALF); R.a[bj] = *(const u32x4*)(AD + (size_t)r * 4096 + col0 + bj * HALF); } }
;     }
;     __device__ __forceinline__ void operator()(AccRef acc, const Unit& u, int wr, int wc, int fr, int fq) const {
;         const int row0 = u.pm * BM + wr * 64 + fr, col0 = u.pn * BM + wc * 32 + 8 * fq;
;         RowIn cur, nxt;
;         if (MODE >= 2) load_row(cur, row0, col0);
; #pragma unroll
;         for (int s = 0; s < 8; ++s) { const int ai = s >> 2, m = s & 3; const int r = row0 + ai * HALF + m * 16; bf16_t* rowp = O + (size_t)r * ldc + col0;
;                 if (MODE >= 2 && s + 1 < 8) load_row(nxt, row0 + ((s + 1) >> 2) * HALF + ((s + 1) & 3) * 16, col0);
;                 float rs = 1.f; if (MODE == 1) rs = __builtin_amdgcn_rsqf(rstd[r] * (1.0f / 4096.0f) + 1e-6f);
;                 float mx = 0.f;
; #pragma unroll
;                 for (int bj = 0; bj < 2; ++bj) { f32x4 v0 = acc[ai][bj][m][0], v1 = acc[ai][bj][m][1];
;                     if (MODE == 1) { v0 = v0 * rs; v1 = v1 * rs;
; #pragma unroll
;                         for (int j = 0; j < 4; ++j) { const float a = v0[j] > 0.f ? v0[j] : 0.f, b = v1[j] > 0.f ? v1[j] : 0.f; v0[j] = a * a; v1[j] = b * b; } }
;                     if (MODE == 2) { f32x4 g0, g1; unpack8(cur.g[bj], g0, g1); v0 = v0 * g0; v1 = v1 * g1; }
;                     if (MODE == 3) { f32x4 g0, g1, a0, a1; unpack8(cur.g[bj], g0, g1); unpack8(cur.a[bj], a0, a1);
;                         v0 = a0 + v0 * g0; v1 = a1 + v1 * g1;
; #pragma unroll
;                         for (int j = 0; j < 4; ++j) mx = fmaxf(mx, fmaxf(fabsf(v0[j]), fabsf(v1[j]))); }
;                     *(u32x4*)(rowp + bj * HALF) = pack8(v0, v1); }
;                 if (MODE == 3) { mx = fmaxf(mx, __shfl_xor(mx, 16)); mx = fmaxf(mx, __shfl_xor(mx, 32)); if (fq == 0) atomicMax(RM + r, __builtin_bit_cast(unsigned, mx)); }
;                 if (MODE >= 2) cur = nxt; }
	v_lshlrev_b32_e32 v76, 16, v66
	v_and_b32_e32 v77, 0xffff0000, v66
	v_lshlrev_b32_e32 v66, 16, v67
	v_and_b32_e32 v67, 0xffff0000, v67
	v_lshlrev_b32_e32 v78, 16, v68
	v_and_b32_e32 v79, 0xffff0000, v68
	v_lshlrev_b32_e32 v72, 16, v73
	v_and_b32_e32 v73, 0xffff0000, v73
	v_lshlrev_b32_e32 v68, 16, v69
	v_and_b32_e32 v69, 0xffff0000, v69
	v_pk_fma_f32 v[40:41], v[40:41], v[48:49], v[66:67]
	v_pk_fma_f32 v[38:39], v[38:39], v[46:47], v[76:77]
	v_pk_fma_f32 v[48:49], v[34:35], v[70:71], v[78:79]
	v_pk_fma_f32 v[46:47], v[36:37], v[72:73], v[68:69]
	v_max_f32_e64 v34, |v38|, |v48|
	v_max_f32_e64 v35, |v39|, |v49|
	v_max3_f32 v34, v80, v34, v35
	v_max_f32_e64 v35, |v40|, |v46|
	v_max_f32_e64 v36, |v41|, |v47|
	v_max3_f32 v34, v34, v35, v36
	ds_bpermute_b32 v35, v180, v34
	v_lshl_add_u64 v[86:87], s[2:3], 0, v[100:101]
	v_lshl_add_u64 v[86:87], v[86:87], 0, v[164:165]
	s_nop 0
	v_cvt_pk_bf16_f32 v44, v44, v45
	s_nop 0
	v_cvt_pk_bf16_f32 v45, v74, v75
	s_waitcnt lgkmcnt(0)
	v_max_f32_e32 v35, v35, v35
	v_max_f32_e32 v34, v34, v35
	ds_bpermute_b32 v35, v181, v34
	global_store_dwordx4 v[86:87], v[42:45], off
	s_nop 0
	v_cvt_pk_bf16_f32 v36, v38, v39
	s_nop 0
	v_cvt_pk_bf16_f32 v37, v40, v41
	s_nop 0
	v_cvt_pk_bf16_f32 v38, v48, v49
	s_nop 0
	v_cvt_pk_bf16_f32 v39, v46, v47
	global_store_dwordx4 v[86:87], v[36:39], off offset:256
	s_and_saveexec_b64 s[26:27], s[6:7]
	s_cbranch_execz .LBB0_1580
	s_waitcnt lgkmcnt(0)
	v_max_f32_e32 v35, v35, v35
	v_max_f32_e32 v34, v34, v34
	v_lshl_add_u64 v[36:37], v[98:99], 2, s[12:13]
	v_max_f32_e32 v34, v34, v35
	global_atomic_umax v[36:37], v34, off
.LBB0_1580:
	s_or_b64 exec, exec, s[26:27]
	v_or_b32_e32 v66, 48, v114
	v_ashrrev_i32_e32 v67, 31, v66
	s_waitcnt lgkmcnt(0)
	v_lshlrev_b64 v[34:35], 14, v[66:67]
	v_lshl_add_u64 v[34:35], s[8:9], 0, v[34:35]
	v_lshlrev_b64 v[68:69], 13, v[66:67]
	v_lshl_add_u64 v[34:35], v[34:35], 0, v[164:165]
	v_add_co_u32_e32 v34, vcc, 0x2000, v34
	v_lshl_add_u64 v[36:37], s[10:11], 0, v[68:69]
	s_nop 0
	v_addc_co_u32_e32 v35, vcc, 0, v35, vcc
	v_lshl_add_u64 v[36:37], v[36:37], 0, v[164:165]
	s_mov_b64 s[98:99], 0x3800
	v_lshl_add_u64 v[246:247], v[248:249], 0, s[98:99]
	global_load_dwordx4 v[46:49], v[246:247], off
	global_load_dwordx4 v[38:41], v[246:247], off offset:1024
	s_mov_b64 s[98:99], 0x3800
	v_lshl_add_u64 v[252:253], v[250:251], 0, s[98:99]
	global_load_dwordx4 v[42:45], v[252:253], off
	s_nop 0
	global_load_dwordx4 v[34:37], v[252:253], off offset:1024
	s_waitcnt vmcnt(9)
	v_lshlrev_b32_e32 v72, 16, v62
	v_and_b32_e32 v73, 0xffff0000, v62
	v_lshlrev_b32_e32 v62, 16, v63
	v_and_b32_e32 v63, 0xffff0000, v63
	v_lshlrev_b32_e32 v74, 16, v64
	v_and_b32_e32 v75, 0xffff0000, v64
	v_lshlrev_b32_e32 v64, 16, v65
	v_and_b32_e32 v65, 0xffff0000, v65
	s_waitcnt vmcnt(7)
	v_lshlrev_b32_e32 v76, 16, v58
	v_and_b32_e32 v77, 0xffff0000, v58
	v_lshlrev_b32_e32 v58, 16, v59
	v_and_b32_e32 v59, 0xffff0000, v59
	v_lshlrev_b32_e32 v78, 16, v60
	v_and_b32_e32 v79, 0xffff0000, v60
	v_lshlrev_b32_e32 v60, 16, v61
	v_and_b32_e32 v61, 0xffff0000, v61
	v_pk_fma_f32 v[32:33], v[32:33], v[62:63], v[58:59]
	v_pk_fma_f32 v[30:31], v[30:31], v[72:73], v[76:77]
	v_pk_fma_f32 v[58:59], v[28:29], v[64:65], v[60:61]
	v_pk_fma_f32 v[28:29], v[26:27], v[74:75], v[78:79]
	v_max_f32_e64 v60, |v33|, |v59|
	v_max_f32_e64 v26, |v30|, |v28|
	v_max_f32_e64 v27, |v31|, |v29|
	v_max3_f32 v26, v26, 0, v27
	v_max_f32_e64 v27, |v32|, |v58|
	v_max3_f32 v64, v26, v27, v60
	s_nop 0
	v_cvt_pk_bf16_f32 v26, v30, v31
	s_nop 0
	v_cvt_pk_bf16_f32 v27, v32, v33
	v_lshlrev_b32_e32 v30, 16, v54
	v_and_b32_e32 v31, 0xffff0000, v54
	v_lshlrev_b32_e32 v32, 16, v55
	v_and_b32_e32 v33, 0xffff0000, v55
	v_lshlrev_b32_e32 v54, 16, v56
	v_and_b32_e32 v55, 0xffff0000, v56
	s_waitcnt vmcnt(6)
	v_lshlrev_b32_e32 v60, 16, v50
	v_and_b32_e32 v61, 0xffff0000, v50
	v_lshlrev_b32_e32 v50, 16, v51
	v_and_b32_e32 v51, 0xffff0000, v51
	v_lshlrev_b32_e32 v62, 16, v52
	v_and_b32_e32 v63, 0xffff0000, v52
	v_lshlrev_b32_e32 v56, 16, v57
	v_and_b32_e32 v57, 0xffff0000, v57
	v_lshlrev_b32_e32 v52, 16, v53
	v_and_b32_e32 v53, 0xffff0000, v53
	v_pk_fma_f32 v[24:25], v[24:25], v[32:33], v[50:51]
	v_pk_fma_f32 v[22:23], v[22:23], v[30:31], v[60:61]
	v_pk_fma_f32 v[32:33], v[18:19], v[54:55], v[62:63]
	v_pk_fma_f32 v[30:31], v[20:21], v[56:57], v[52:53]
	v_max_f32_e64 v18, |v22|, |v32|
	v_max_f32_e64 v19, |v23|, |v33|
	v_max3_f32 v18, v64, v18, v19
	v_max_f32_e64 v19, |v24|, |v30|
	v_max_f32_e64 v20, |v25|, |v31|
	v_max3_f32 v18, v18, v19, v20
	ds_bpermute_b32 v19, v180, v18
	v_lshl_add_u64 v[70:71], s[2:3], 0, v[84:85]
	v_lshl_add_u64 v[70:71], v[70:71], 0, v[164:165]
	s_nop 0
	v_cvt_pk_bf16_f32 v28, v28, v29
	s_nop 0
	v_cvt_pk_bf16_f32 v29, v58, v59
	s_waitcnt lgkmcnt(0)
	v_max_f32_e32 v19, v19, v19
	v_max_f32_e32 v18, v18, v19
	ds_bpermute_b32 v19, v181, v18
	global_store_dwordx4 v[70:71], v[26:29], off
	s_nop 0
	v_cvt_pk_bf16_f32 v20, v22, v23
	s_nop 0
	v_cvt_pk_bf16_f32 v21, v24, v25
	s_nop 0
	v_cvt_pk_bf16_f32 v22, v32, v33
	s_nop 0
	v_cvt_pk_bf16_f32 v23, v30, v31
	global_store_dwordx4 v[70:71], v[20:23], off offset:256
	s_and_saveexec_b64 s[26:27], s[6:7]
	s_cbranch_execz .LBB0_1582
	s_waitcnt lgkmcnt(0)
	v_max_f32_e32 v19, v19, v19
	v_max_f32_e32 v18, v18, v18
	v_lshl_add_u64 v[20:21], v[82:83], 2, s[12:13]
	v_max_f32_e32 v18, v18, v19
	global_atomic_umax v[20:21], v18, off
